# A/B of the GEMM template's per-cluster s_setprio 1 flips (all set to 0 in the six GEMM mainloops)
# baseline (speedup 1.0000x reference)
; #define PG8_STAGE(bufoff, gbase, voff) do { _Pragma("unroll") for (int _i = 0; _i < 2; ++_i) \
;         __builtin_amdgcn_global_load_lds((const unsigned*)((const char*)(gbase) + (voff)[_i]), (LAS unsigned*)(lds + (bufoff) + ldsw + _i * 8192), 16, 0, 0); } while (0)
; #define PG8_LDA(dst, b, h) do { _Pragma("unroll") for (int m = 0; m < 4; ++m) _Pragma("unroll") for (int k = 0; k < 2; ++k) dst[m][k] = *(const LAS bf16x8*)(lds + PG8_SA(b, h) + aoff + m * 2048 + k * 1024); } while (0)
; #define PG8_LDB(dst, b, h) do { _Pragma("unroll") for (int n = 0; n < 2; ++n) _Pragma("unroll") for (int k = 0; k < 2; ++k) dst[n][k] = *(const LAS bf16x8*)(lds + PG8_SB(b, h) + boff + n * 2048 + k * 1024); } while (0)
; #define PG8_MMA(ai, bj, At, Bt) do { __builtin_amdgcn_s_setprio(1); _Pragma("unroll") for (int m = 0; m < 4; ++m) _Pragma("unroll") for (int n = 0; n < 2; ++n) _Pragma("unroll") for (int k = 0; k < 2; ++k) \
;         acc[ai][bj][m][n] = __builtin_amdgcn_mfma_f32_16x16x32_bf16(Bt[n][k], At[m][k], acc[ai][bj][m][n], 0, 0, 0); __builtin_amdgcn_s_setprio(0); } while (0)
; #define PG8_WAIT_V(n) asm volatile("s_waitcnt vmcnt(" #n ")" ::: "memory")
; #define PG8_WAIT_L(n) asm volatile("s_waitcnt lgkmcnt(" #n ")" ::: "memory")
; #define PG8_BAR __builtin_amdgcn_s_barrier()
; #define PG8_SCHED __builtin_amdgcn_sched_barrier(0)
; template <class Epi, class Sched>
; __device__ __forceinline__ void gemm_phase(LAS unsigned char* lds, const Gemm g, const Sched& S, const Epi& E) {
;     ...
;             PG8_LDB(B0, 0, 0); PG8_LDB(B1, 0, 1); PG8_SCHED; PG8_LDA(At, 0, 0); PG8_STAGE(PG8_SA(1, 1), a1 + hA, voffA);
;             PG8_WAIT_V(8); PG8_WAIT_L(0); PG8_BAR; PG8_MMA(0, 0, At, B0); PG8_MMA(0, 1, At, B1); PG8_BAR; PG8_SCHED;
;             PG8_LDA(At, 0, 1); PG8_STAGE(PG8_SB(0, 0), b2, voffB); PG8_STAGE(PG8_SB(0, 1), b2 + hB, voffB); PG8_STAGE(PG8_SA(0, 0), a2, voffA);
;             PG8_WAIT_V(8); PG8_WAIT_L(0); PG8_BAR; PG8_MMA(1, 0, At, B0); PG8_MMA(1, 1, At, B1); PG8_BAR; PG8_SCHED;
.LBB0_248:
	ds_read_b128 v[128:131], v165
	ds_read_b128 v[132:135], v165 offset:1024
	ds_read_b128 v[136:139], v165 offset:2048
	ds_read_b128 v[154:157], v165 offset:3072
	ds_read_b128 v[158:161], v166
	ds_read_b128 v[170:173], v166 offset:1024
	ds_read_b128 v[174:177], v166 offset:2048
	ds_read_b128 v[178:181], v166 offset:3072
	s_add_u32 s0, s4, 0xfff80080
	s_addc_u32 s1, s5, -1
	s_cmp_eq_u32 s45, 28
	s_cselect_b32 s7, s3, s1
	s_cselect_b32 s6, s8, s0
	s_cselect_b32 s1, s9, s43
	s_cselect_b32 s0, s22, s35
	v_lshl_add_u64 v[214:215], s[4:5], 0, v[148:149]
	s_add_i32 m0, s19, 0xc000
	ds_read_b128 v[182:185], v167
	ds_read_b128 v[186:189], v167 offset:1024
	ds_read_b128 v[190:193], v167 offset:2048
	ds_read_b128 v[194:197], v167 offset:3072
	ds_read_b128 v[198:201], v167 offset:4096
	ds_read_b128 v[202:205], v167 offset:5120
	ds_read_b128 v[206:209], v167 offset:6144
	ds_read_b128 v[210:213], v167 offset:7168
	global_load_lds_dwordx4 v[214:215], off
	v_lshl_add_u64 v[214:215], s[4:5], 0, v[150:151]
	s_add_i32 m0, s19, 0xe000
	s_nop 0
	global_load_lds_dwordx4 v[214:215], off
	s_waitcnt vmcnt(8)
	s_waitcnt lgkmcnt(0)
	s_barrier
	s_setprio 0
	s_waitcnt lgkmcnt(0)
	v_mfma_f32_16x16x32_bf16 v[124:127], v[128:131], v[182:185], v[124:127]
	v_mfma_f32_16x16x32_bf16 v[120:123], v[136:139], v[182:185], v[120:123]
	v_mfma_f32_16x16x32_bf16 v[108:111], v[128:131], v[190:193], v[108:111]
	v_mfma_f32_16x16x32_bf16 v[104:107], v[136:139], v[190:193], v[104:107]
	v_mfma_f32_16x16x32_bf16 v[92:95], v[128:131], v[198:201], v[92:95]
	v_mfma_f32_16x16x32_bf16 v[88:91], v[136:139], v[198:201], v[88:91]
	v_mfma_f32_16x16x32_bf16 v[76:79], v[128:131], v[206:209], v[76:79]
	v_mfma_f32_16x16x32_bf16 v[72:75], v[136:139], v[206:209], v[72:75]
	v_mfma_f32_16x16x32_bf16 v[124:127], v[132:135], v[186:189], v[124:127]
	v_mfma_f32_16x16x32_bf16 v[120:123], v[154:157], v[186:189], v[120:123]
	v_mfma_f32_16x16x32_bf16 v[108:111], v[132:135], v[194:197], v[108:111]
	v_mfma_f32_16x16x32_bf16 v[104:107], v[154:157], v[194:197], v[104:107]
	v_mfma_f32_16x16x32_bf16 v[92:95], v[132:135], v[202:205], v[92:95]
	v_mfma_f32_16x16x32_bf16 v[88:91], v[154:157], v[202:205], v[88:91]
	v_mfma_f32_16x16x32_bf16 v[76:79], v[132:135], v[210:213], v[76:79]
	v_mfma_f32_16x16x32_bf16 v[72:75], v[154:157], v[210:213], v[72:75]
	s_setprio 0
	s_setprio 0
	v_mfma_f32_16x16x32_bf16 v[116:119], v[158:161], v[182:185], v[116:119]
	v_mfma_f32_16x16x32_bf16 v[112:115], v[174:177], v[182:185], v[112:115]
	v_mfma_f32_16x16x32_bf16 v[100:103], v[158:161], v[190:193], v[100:103]
	v_mfma_f32_16x16x32_bf16 v[96:99], v[174:177], v[190:193], v[96:99]
	v_mfma_f32_16x16x32_bf16 v[84:87], v[158:161], v[198:201], v[84:87]
	v_mfma_f32_16x16x32_bf16 v[80:83], v[174:177], v[198:201], v[80:83]
	v_mfma_f32_16x16x32_bf16 v[68:71], v[158:161], v[206:209], v[68:71]
	v_mfma_f32_16x16x32_bf16 v[64:67], v[174:177], v[206:209], v[64:67]
	v_mfma_f32_16x16x32_bf16 v[116:119], v[170:173], v[186:189], v[116:119]
	v_mfma_f32_16x16x32_bf16 v[112:115], v[178:181], v[186:189], v[112:115]
	v_mfma_f32_16x16x32_bf16 v[100:103], v[170:173], v[194:197], v[100:103]
	v_mfma_f32_16x16x32_bf16 v[96:99], v[178:181], v[194:197], v[96:99]
	v_mfma_f32_16x16x32_bf16 v[84:87], v[170:173], v[202:205], v[84:87]
	v_mfma_f32_16x16x32_bf16 v[80:83], v[178:181], v[202:205], v[80:83]
	v_mfma_f32_16x16x32_bf16 v[68:71], v[170:173], v[210:213], v[68:71]
	v_mfma_f32_16x16x32_bf16 v[64:67], v[178:181], v[210:213], v[64:67]
	s_setprio 0
	s_barrier
	s_add_i32 s26, s83, s18
	v_lshl_add_u64 v[214:215], s[0:1], 0, v[142:143]
	s_mov_b32 m0, s26
	ds_read_b128 v[182:185], v167 offset:16384
	ds_read_b128 v[186:189], v167 offset:17408
	ds_read_b128 v[190:193], v167 offset:18432
	ds_read_b128 v[194:197], v167 offset:19456
	ds_read_b128 v[198:201], v167 offset:20480
	ds_read_b128 v[202:205], v167 offset:21504
	ds_read_b128 v[206:209], v167 offset:22528
	ds_read_b128 v[210:213], v167 offset:23552
	global_load_lds_dwordx4 v[214:215], off
	s_add_i32 m0, s26, 0x2000
	s_add_u32 s26, s0, 0x80000
	v_lshl_add_u64 v[216:217], s[0:1], 0, v[146:147]
	s_addc_u32 s27, s1, 0
	s_add_i32 s86, s94, s18
	global_load_lds_dwordx4 v[216:217], off
	v_lshl_add_u64 v[220:221], s[26:27], 0, v[142:143]
	s_mov_b32 m0, s86
	v_lshl_add_u64 v[222:223], s[6:7], 0, v[144:145]
	global_load_lds_dwordx4 v[220:221], off
	v_lshl_add_u64 v[220:221], s[26:27], 0, v[146:147]
	s_add_i32 m0, s86, 0x2000
	s_nop 0
	global_load_lds_dwordx4 v[220:221], off
	v_lshl_add_u64 v[220:221], s[6:7], 0, v[140:141]
	s_mov_b32 m0, s19
	s_nop 0
	global_load_lds_dwordx4 v[220:221], off
	s_mov_b32 m0, s74
	s_nop 0
	global_load_lds_dwordx4 v[222:223], off
	s_waitcnt vmcnt(8)
	s_waitcnt lgkmcnt(0)
	s_barrier
; #define PG8_STAGE(bufoff, gbase, voff) do { _Pragma("unroll") for (int _i = 0; _i < 2; ++_i) \
;         __builtin_amdgcn_global_load_lds((const unsigned*)((const char*)(gbase) + (voff)[_i]), (LAS unsigned*)(lds + (bufoff) + ldsw + _i * 8192), 16, 0, 0); } while (0)
; #define PG8_LDA(dst, b, h) do { _Pragma("unroll") for (int m = 0; m < 4; ++m) _Pragma("unroll") for (int k = 0; k < 2; ++k) dst[m][k] = *(const LAS bf16x8*)(lds + PG8_SA(b, h) + aoff + m * 2048 + k * 1024); } while (0)
; #define PG8_LDB(dst, b, h) do { _Pragma("unroll") for (int n = 0; n < 2; ++n) _Pragma("unroll") for (int k = 0; k < 2; ++k) dst[n][k] = *(const LAS bf16x8*)(lds + PG8_SB(b, h) + boff + n * 2048 + k * 1024); } while (0)
; #define PG8_MMA(ai, bj, At, Bt) do { __builtin_amdgcn_s_setprio(1); _Pragma("unroll") for (int m = 0; m < 4; ++m) _Pragma("unroll") for (int n = 0; n < 2; ++n) _Pragma("unroll") for (int k = 0; k < 2; ++k) \
;         acc[ai][bj][m][n] = __builtin_amdgcn_mfma_f32_16x16x32_bf16(Bt[n][k], At[m][k], acc[ai][bj][m][n], 0, 0, 0); __builtin_amdgcn_s_setprio(0); } while (0)
; #define PG8_WAIT_V(n) asm volatile("s_waitcnt vmcnt(" #n ")" ::: "memory")
; #define PG8_WAIT_L(n) asm volatile("s_waitcnt lgkmcnt(" #n ")" ::: "memory")
; #define PG8_BAR __builtin_amdgcn_s_barrier()
; #define PG8_SCHED __builtin_amdgcn_sched_barrier(0)
; template <class Epi, class Sched>
; __device__ __forceinline__ void gemm_phase(LAS unsigned char* lds, const Gemm g, const Sched& S, const Epi& E) {
;     ...
;             PG8_WAIT_V(8); PG8_WAIT_L(0); PG8_BAR; PG8_MMA(1, 0, At, B0); PG8_MMA(1, 1, At, B1); PG8_BAR; PG8_SCHED;
;             PG8_LDB(B0, 1, 0); PG8_LDB(B1, 1, 1); PG8_SCHED; PG8_LDA(At, 1, 0); PG8_STAGE(PG8_SA(0, 1), a2 + hA, voffA);
;             PG8_WAIT_V(8); PG8_WAIT_L(0); PG8_BAR; PG8_MMA(0, 0, At, B0); PG8_MMA(0, 1, At, B1); PG8_BAR; PG8_SCHED;
	s_setprio 0
	s_waitcnt lgkmcnt(0)
	v_mfma_f32_16x16x32_bf16 v[60:63], v[128:131], v[182:185], v[60:63]
	v_mfma_f32_16x16x32_bf16 v[56:59], v[136:139], v[182:185], v[56:59]
	v_mfma_f32_16x16x32_bf16 v[44:47], v[128:131], v[190:193], v[44:47]
	v_mfma_f32_16x16x32_bf16 v[40:43], v[136:139], v[190:193], v[40:43]
	v_mfma_f32_16x16x32_bf16 v[28:31], v[128:131], v[198:201], v[28:31]
	v_mfma_f32_16x16x32_bf16 v[24:27], v[136:139], v[198:201], v[24:27]
	v_mfma_f32_16x16x32_bf16 v[12:15], v[128:131], v[206:209], v[12:15]
	v_mfma_f32_16x16x32_bf16 v[8:11], v[136:139], v[206:209], v[8:11]
	v_mfma_f32_16x16x32_bf16 v[60:63], v[132:135], v[186:189], v[60:63]
	v_mfma_f32_16x16x32_bf16 v[56:59], v[154:157], v[186:189], v[56:59]
	v_mfma_f32_16x16x32_bf16 v[44:47], v[132:135], v[194:197], v[44:47]
	v_mfma_f32_16x16x32_bf16 v[40:43], v[154:157], v[194:197], v[40:43]
	v_mfma_f32_16x16x32_bf16 v[28:31], v[132:135], v[202:205], v[28:31]
	v_mfma_f32_16x16x32_bf16 v[24:27], v[154:157], v[202:205], v[24:27]
	v_mfma_f32_16x16x32_bf16 v[12:15], v[132:135], v[210:213], v[12:15]
	v_mfma_f32_16x16x32_bf16 v[8:11], v[154:157], v[210:213], v[8:11]
	s_setprio 0
	s_setprio 0
	v_mfma_f32_16x16x32_bf16 v[52:55], v[158:161], v[182:185], v[52:55]
	v_mfma_f32_16x16x32_bf16 v[48:51], v[174:177], v[182:185], v[48:51]
	v_mfma_f32_16x16x32_bf16 v[36:39], v[158:161], v[190:193], v[36:39]
	v_mfma_f32_16x16x32_bf16 v[32:35], v[174:177], v[190:193], v[32:35]
	v_mfma_f32_16x16x32_bf16 v[20:23], v[158:161], v[198:201], v[20:23]
	v_mfma_f32_16x16x32_bf16 v[16:19], v[174:177], v[198:201], v[16:19]
	v_mfma_f32_16x16x32_bf16 v[4:7], v[158:161], v[206:209], v[4:7]
	v_mfma_f32_16x16x32_bf16 v[0:3], v[174:177], v[206:209], v[0:3]
	v_mfma_f32_16x16x32_bf16 v[52:55], v[170:173], v[186:189], v[52:55]
	v_mfma_f32_16x16x32_bf16 v[48:51], v[178:181], v[186:189], v[48:51]
	v_mfma_f32_16x16x32_bf16 v[36:39], v[170:173], v[194:197], v[36:39]
	v_mfma_f32_16x16x32_bf16 v[32:35], v[178:181], v[194:197], v[32:35]
	v_mfma_f32_16x16x32_bf16 v[20:23], v[170:173], v[202:205], v[20:23]
	v_mfma_f32_16x16x32_bf16 v[16:19], v[178:181], v[202:205], v[16:19]
	v_mfma_f32_16x16x32_bf16 v[4:7], v[170:173], v[210:213], v[4:7]
	v_mfma_f32_16x16x32_bf16 v[0:3], v[178:181], v[210:213], v[0:3]
	s_setprio 0
	s_barrier
	s_add_i32 s26, 0, 0x18000
	s_add_i32 s27, 0, 0x1c000
	v_add_u32_e32 v154, s26, v164
	v_add_u32_e32 v178, s27, v164
	ds_read_b128 v[128:131], v154
	ds_read_b128 v[132:135], v154 offset:1024
	ds_read_b128 v[136:139], v154 offset:2048
	ds_read_b128 v[154:157], v154 offset:3072
	ds_read_b128 v[158:161], v178
	ds_read_b128 v[170:173], v178 offset:1024
	ds_read_b128 v[174:177], v178 offset:2048
	ds_read_b128 v[178:181], v178 offset:3072
	s_add_u32 s6, s6, 0x80000
	s_addc_u32 s7, s7, 0
	s_mov_b32 m0, s75
	v_lshl_add_u64 v[224:225], s[6:7], 0, v[140:141]
	ds_read_b128 v[182:185], v167 offset:32768
	ds_read_b128 v[186:189], v167 offset:33792
	ds_read_b128 v[190:193], v167 offset:34816
	ds_read_b128 v[194:197], v167 offset:35840
	ds_read_b128 v[198:201], v167 offset:36864
	ds_read_b128 v[202:205], v167 offset:37888
	ds_read_b128 v[206:209], v167 offset:38912
	ds_read_b128 v[210:213], v167 offset:39936
	global_load_lds_dwordx4 v[224:225], off
	v_lshl_add_u64 v[224:225], s[6:7], 0, v[144:145]
	s_mov_b32 m0, s76
	s_nop 0
	global_load_lds_dwordx4 v[224:225], off
	s_waitcnt vmcnt(8)
	s_waitcnt lgkmcnt(0)
	s_barrier
	s_setprio 0
	s_waitcnt lgkmcnt(0)
	v_mfma_f32_16x16x32_bf16 v[124:127], v[128:131], v[182:185], v[124:127]
	v_mfma_f32_16x16x32_bf16 v[120:123], v[136:139], v[182:185], v[120:123]
	v_mfma_f32_16x16x32_bf16 v[108:111], v[128:131], v[190:193], v[108:111]
	v_mfma_f32_16x16x32_bf16 v[104:107], v[136:139], v[190:193], v[104:107]
	v_mfma_f32_16x16x32_bf16 v[92:95], v[128:131], v[198:201], v[92:95]
	v_mfma_f32_16x16x32_bf16 v[88:91], v[136:139], v[198:201], v[88:91]
	v_mfma_f32_16x16x32_bf16 v[76:79], v[128:131], v[206:209], v[76:79]
	v_mfma_f32_16x16x32_bf16 v[72:75], v[136:139], v[206:209], v[72:75]
	v_mfma_f32_16x16x32_bf16 v[124:127], v[132:135], v[186:189], v[124:127]
	v_mfma_f32_16x16x32_bf16 v[120:123], v[154:157], v[186:189], v[120:123]
	v_mfma_f32_16x16x32_bf16 v[108:111], v[132:135], v[194:197], v[108:111]
	v_mfma_f32_16x16x32_bf16 v[104:107], v[154:157], v[194:197], v[104:107]
	v_mfma_f32_16x16x32_bf16 v[92:95], v[132:135], v[202:205], v[92:95]
	v_mfma_f32_16x16x32_bf16 v[88:91], v[154:157], v[202:205], v[88:91]
	v_mfma_f32_16x16x32_bf16 v[76:79], v[132:135], v[210:213], v[76:79]
	v_mfma_f32_16x16x32_bf16 v[72:75], v[154:157], v[210:213], v[72:75]
	s_setprio 0
	s_setprio 0
	v_mfma_f32_16x16x32_bf16 v[116:119], v[158:161], v[182:185], v[116:119]
	v_mfma_f32_16x16x32_bf16 v[112:115], v[174:177], v[182:185], v[112:115]
	v_mfma_f32_16x16x32_bf16 v[100:103], v[158:161], v[190:193], v[100:103]
	v_mfma_f32_16x16x32_bf16 v[96:99], v[174:177], v[190:193], v[96:99]
	v_mfma_f32_16x16x32_bf16 v[84:87], v[158:161], v[198:201], v[84:87]
	v_mfma_f32_16x16x32_bf16 v[80:83], v[174:177], v[198:201], v[80:83]
	v_mfma_f32_16x16x32_bf16 v[68:71], v[158:161], v[206:209], v[68:71]
	v_mfma_f32_16x16x32_bf16 v[64:67], v[174:177], v[206:209], v[64:67]
	v_mfma_f32_16x16x32_bf16 v[116:119], v[170:173], v[186:189], v[116:119]
	v_mfma_f32_16x16x32_bf16 v[112:115], v[178:181], v[186:189], v[112:115]
	v_mfma_f32_16x16x32_bf16 v[100:103], v[170:173], v[194:197], v[100:103]
	v_mfma_f32_16x16x32_bf16 v[96:99], v[178:181], v[194:197], v[96:99]
	v_mfma_f32_16x16x32_bf16 v[84:87], v[170:173], v[202:205], v[84:87]
	v_mfma_f32_16x16x32_bf16 v[80:83], v[178:181], v[202:205], v[80:83]
	v_mfma_f32_16x16x32_bf16 v[68:71], v[170:173], v[210:213], v[68:71]
	v_mfma_f32_16x16x32_bf16 v[64:67], v[178:181], v[210:213], v[64:67]
	s_setprio 0
	s_barrier
; #define PG8_STAGE(bufoff, gbase, voff) do { _Pragma("unroll") for (int _i = 0; _i < 2; ++_i) \
;         __builtin_amdgcn_global_load_lds((const unsigned*)((const char*)(gbase) + (voff)[_i]), (LAS unsigned*)(lds + (bufoff) + ldsw + _i * 8192), 16, 0, 0); } while (0)
; #define PG8_LDA(dst, b, h) do { _Pragma("unroll") for (int m = 0; m < 4; ++m) _Pragma("unroll") for (int k = 0; k < 2; ++k) dst[m][k] = *(const LAS bf16x8*)(lds + PG8_SA(b, h) + aoff + m * 2048 + k * 1024); } while (0)
; #define PG8_MMA(ai, bj, At, Bt) do { __builtin_amdgcn_s_setprio(1); _Pragma("unroll") for (int m = 0; m < 4; ++m) _Pragma("unroll") for (int n = 0; n < 2; ++n) _Pragma("unroll") for (int k = 0; k < 2; ++k) \
;         acc[ai][bj][m][n] = __builtin_amdgcn_mfma_f32_16x16x32_bf16(Bt[n][k], At[m][k], acc[ai][bj][m][n], 0, 0, 0); __builtin_amdgcn_s_setprio(0); } while (0)
; #define PG8_WAIT_V(n) asm volatile("s_waitcnt vmcnt(" #n ")" ::: "memory")
; #define PG8_WAIT_L(n) asm volatile("s_waitcnt lgkmcnt(" #n ")" ::: "memory")
; #define PG8_BAR __builtin_amdgcn_s_barrier()
; #define PG8_SCHED __builtin_amdgcn_sched_barrier(0)
; template <class Epi, class Sched>
; __device__ __forceinline__ void gemm_phase(LAS unsigned char* lds, const Gemm g, const Sched& S, const Epi& E) {
;     ...
;             PG8_LDA(At, 1, 1); PG8_STAGE(PG8_SB(1, 0), b3, voffB); PG8_STAGE(PG8_SB(1, 1), b3 + hB, voffB); PG8_STAGE(PG8_SA(1, 0), a3, voffA);
;             PG8_WAIT_V(8); PG8_WAIT_L(0); PG8_BAR; PG8_MMA(1, 0, At, B0); PG8_MMA(1, 1, At, B1); PG8_BAR; PG8_SCHED;
;         }
;         if (wr == 0) PG8_BAR;
	s_add_i32 s6, s26, s18
	v_lshl_add_u64 v[214:215], v[214:215], 0, s[28:29]
	s_mov_b32 m0, s6
	ds_read_b128 v[182:185], v167 offset:49152
	ds_read_b128 v[186:189], v167 offset:50176
	ds_read_b128 v[190:193], v167 offset:51200
	ds_read_b128 v[194:197], v167 offset:52224
	ds_read_b128 v[198:201], v167 offset:53248
	ds_read_b128 v[202:205], v167 offset:54272
	ds_read_b128 v[206:209], v167 offset:55296
	ds_read_b128 v[210:213], v167 offset:56320
	global_load_lds_dwordx4 v[214:215], off
	s_add_i32 m0, s6, 0x2000
	s_add_u32 s0, s0, 0x80080
	v_lshl_add_u64 v[214:215], v[216:217], 0, s[28:29]
	s_addc_u32 s1, s1, 0
	s_add_i32 s6, s27, s18
	global_load_lds_dwordx4 v[214:215], off
	v_lshl_add_u64 v[214:215], s[0:1], 0, v[142:143]
	s_mov_b32 m0, s6
	s_nop 0
	global_load_lds_dwordx4 v[214:215], off
	v_lshl_add_u64 v[214:215], s[0:1], 0, v[146:147]
	s_add_i32 m0, s6, 0x2000
	s_nop 0
	global_load_lds_dwordx4 v[214:215], off
	v_lshl_add_u64 v[214:215], v[220:221], 0, s[28:29]
	s_mov_b32 m0, s97
	s_nop 0
	global_load_lds_dwordx4 v[214:215], off
	v_lshl_add_u64 v[214:215], v[222:223], 0, s[28:29]
	s_mov_b32 m0, s33
	s_nop 0
	global_load_lds_dwordx4 v[214:215], off
	s_waitcnt vmcnt(8)
	s_waitcnt lgkmcnt(0)
	s_barrier
	s_setprio 0
	s_waitcnt lgkmcnt(0)
	v_mfma_f32_16x16x32_bf16 v[60:63], v[128:131], v[182:185], v[60:63]
	v_mfma_f32_16x16x32_bf16 v[56:59], v[136:139], v[182:185], v[56:59]
	v_mfma_f32_16x16x32_bf16 v[44:47], v[128:131], v[190:193], v[44:47]
	v_mfma_f32_16x16x32_bf16 v[40:43], v[136:139], v[190:193], v[40:43]
	v_mfma_f32_16x16x32_bf16 v[28:31], v[128:131], v[198:201], v[28:31]
	v_mfma_f32_16x16x32_bf16 v[24:27], v[136:139], v[198:201], v[24:27]
	v_mfma_f32_16x16x32_bf16 v[12:15], v[128:131], v[206:209], v[12:15]
	v_mfma_f32_16x16x32_bf16 v[8:11], v[136:139], v[206:209], v[8:11]
	v_mfma_f32_16x16x32_bf16 v[60:63], v[132:135], v[186:189], v[60:63]
	v_mfma_f32_16x16x32_bf16 v[56:59], v[154:157], v[186:189], v[56:59]
	v_mfma_f32_16x16x32_bf16 v[44:47], v[132:135], v[194:197], v[44:47]
	v_mfma_f32_16x16x32_bf16 v[40:43], v[154:157], v[194:197], v[40:43]
	v_mfma_f32_16x16x32_bf16 v[28:31], v[132:135], v[202:205], v[28:31]
	v_mfma_f32_16x16x32_bf16 v[24:27], v[154:157], v[202:205], v[24:27]
	v_mfma_f32_16x16x32_bf16 v[12:15], v[132:135], v[210:213], v[12:15]
	v_mfma_f32_16x16x32_bf16 v[8:11], v[154:157], v[210:213], v[8:11]
	s_setprio 0
	s_setprio 0
	v_mfma_f32_16x16x32_bf16 v[52:55], v[158:161], v[182:185], v[52:55]
	v_mfma_f32_16x16x32_bf16 v[48:51], v[174:177], v[182:185], v[48:51]
	v_mfma_f32_16x16x32_bf16 v[36:39], v[158:161], v[190:193], v[36:39]
	v_mfma_f32_16x16x32_bf16 v[32:35], v[174:177], v[190:193], v[32:35]
	v_mfma_f32_16x16x32_bf16 v[20:23], v[158:161], v[198:201], v[20:23]
	v_mfma_f32_16x16x32_bf16 v[16:19], v[174:177], v[198:201], v[16:19]
	v_mfma_f32_16x16x32_bf16 v[4:7], v[158:161], v[206:209], v[4:7]
	v_mfma_f32_16x16x32_bf16 v[0:3], v[174:177], v[206:209], v[0:3]
	v_mfma_f32_16x16x32_bf16 v[52:55], v[170:173], v[186:189], v[52:55]
	v_mfma_f32_16x16x32_bf16 v[48:51], v[178:181], v[186:189], v[48:51]
	v_mfma_f32_16x16x32_bf16 v[36:39], v[170:173], v[194:197], v[36:39]
	v_mfma_f32_16x16x32_bf16 v[32:35], v[178:181], v[194:197], v[32:35]
	v_mfma_f32_16x16x32_bf16 v[20:23], v[170:173], v[202:205], v[20:23]
	v_mfma_f32_16x16x32_bf16 v[16:19], v[178:181], v[202:205], v[16:19]
	v_mfma_f32_16x16x32_bf16 v[4:7], v[170:173], v[210:213], v[4:7]
	v_mfma_f32_16x16x32_bf16 v[0:3], v[178:181], v[210:213], v[0:3]
	s_setprio 0
	s_barrier
	s_add_i32 s45, s45, 2
	s_add_u32 s4, s4, 0x100
	s_addc_u32 s5, s5, 0
	s_add_u32 s35, s35, 0x100
	s_addc_u32 s43, s43, 0
	s_cmp_gt_u32 s45, 29
	s_cbranch_scc0 .LBB0_248
	s_and_b64 vcc, exec, s[38:39]
	s_cbranch_vccz .LBB0_251
	s_barrier

; #define PG8_STAGE(bufoff, gbase, voff) do { _Pragma("unroll") for (int _i = 0; _i < 2; ++_i) \
;         __builtin_amdgcn_global_load_lds((const unsigned*)((const char*)(gbase) + (voff)[_i]), (LAS unsigned*)(lds + (bufoff) + ldsw + _i * 8192), 16, 0, 0); } while (0)
; #define PG8_LDA(dst, b, h) do { _Pragma("unroll") for (int m = 0; m < 4; ++m) _Pragma("unroll") for (int k = 0; k < 2; ++k) dst[m][k] = *(const LAS bf16x8*)(lds + PG8_SA(b, h) + aoff + m * 2048 + k * 1024); } while (0)
; #define PG8_LDB(dst, b, h) do { _Pragma("unroll") for (int n = 0; n < 2; ++n) _Pragma("unroll") for (int k = 0; k < 2; ++k) dst[n][k] = *(const LAS bf16x8*)(lds + PG8_SB(b, h) + boff + n * 2048 + k * 1024); } while (0)
; #define PG8_MMA(ai, bj, At, Bt) do { __builtin_amdgcn_s_setprio(1); _Pragma("unroll") for (int m = 0; m < 4; ++m) _Pragma("unroll") for (int n = 0; n < 2; ++n) _Pragma("unroll") for (int k = 0; k < 2; ++k) \
;         acc[ai][bj][m][n] = __builtin_amdgcn_mfma_f32_16x16x32_bf16(Bt[n][k], At[m][k], acc[ai][bj][m][n], 0, 0, 0); __builtin_amdgcn_s_setprio(0); } while (0)
; #define PG8_WAIT_V(n) asm volatile("s_waitcnt vmcnt(" #n ")" ::: "memory")
; #define PG8_WAIT_L(n) asm volatile("s_waitcnt lgkmcnt(" #n ")" ::: "memory")
; #define PG8_BAR __builtin_amdgcn_s_barrier()
; #define PG8_SCHED __builtin_amdgcn_sched_barrier(0)
; template <class Epi, class Sched>
; __device__ __forceinline__ void gemm_phase(LAS unsigned char* lds, const Gemm g, const Sched& S, const Epi& E) {
;     ...
;             PG8_LDB(B0, 0, 0); PG8_LDB(B1, 0, 1); PG8_SCHED; PG8_LDA(At, 0, 0); PG8_STAGE(PG8_SA(1, 1), a1 + hA, voffA);
;             PG8_WAIT_V(8); PG8_WAIT_L(0); PG8_BAR; PG8_MMA(0, 0, At, B0); PG8_MMA(0, 1, At, B1); PG8_BAR; PG8_SCHED;
;             PG8_LDA(At, 0, 1); PG8_STAGE(PG8_SB(0, 0), b2, voffB); PG8_STAGE(PG8_SB(0, 1), b2 + hB, voffB); PG8_STAGE(PG8_SA(0, 0), a2, voffA);
;             PG8_WAIT_V(8); PG8_WAIT_L(0); PG8_BAR; PG8_MMA(1, 0, At, B0); PG8_MMA(1, 1, At, B1); PG8_BAR; PG8_SCHED;
.LBB0_725:
	ds_read_b128 v[144:147], v170
	ds_read_b128 v[174:177], v170 offset:1024
	ds_read_b128 v[178:181], v170 offset:2048
	ds_read_b128 v[182:185], v170 offset:3072
	ds_read_b128 v[186:189], v171
	ds_read_b128 v[190:193], v171 offset:1024
	ds_read_b128 v[194:197], v171 offset:2048
	ds_read_b128 v[198:201], v171 offset:3072
	s_add_u32 s0, s4, 0xffe40080
	s_addc_u32 s1, s5, -1
	s_cmp_eq_u32 s62, 28
	s_cselect_b32 s19, s39, s1
	s_cselect_b32 s18, s38, s0
	s_cselect_b32 s1, s31, s43
	s_cselect_b32 s0, s61, s42
	v_lshl_add_u64 v[148:149], s[4:5], 0, v[136:137]
	s_add_i32 m0, s47, 0xc000
	ds_read_b128 v[202:205], v172
	ds_read_b128 v[206:209], v172 offset:1024
	ds_read_b128 v[210:213], v172 offset:2048
	ds_read_b128 v[214:217], v172 offset:3072
	ds_read_b128 v[220:223], v172 offset:4096
	ds_read_b128 v[224:227], v172 offset:5120
	ds_read_b128 v[228:231], v172 offset:6144
	ds_read_b128 v[232:235], v172 offset:7168
	global_load_lds_dwordx4 v[148:149], off
	v_lshl_add_u64 v[148:149], s[4:5], 0, v[138:139]
	s_add_i32 m0, s47, 0xe000
	s_nop 0
	global_load_lds_dwordx4 v[148:149], off
	s_waitcnt vmcnt(8)
	s_waitcnt lgkmcnt(0)
	s_barrier
	s_setprio 0
	s_waitcnt lgkmcnt(0)
	v_mfma_f32_16x16x32_bf16 v[124:127], v[144:147], v[202:205], v[124:127]
	v_mfma_f32_16x16x32_bf16 v[120:123], v[178:181], v[202:205], v[120:123]
	v_mfma_f32_16x16x32_bf16 v[112:115], v[144:147], v[210:213], v[112:115]
	v_mfma_f32_16x16x32_bf16 v[104:107], v[178:181], v[210:213], v[104:107]
	v_mfma_f32_16x16x32_bf16 v[96:99], v[144:147], v[220:223], v[96:99]
	v_mfma_f32_16x16x32_bf16 v[88:91], v[178:181], v[220:223], v[88:91]
	v_mfma_f32_16x16x32_bf16 v[80:83], v[144:147], v[228:231], v[80:83]
	v_mfma_f32_16x16x32_bf16 v[72:75], v[178:181], v[228:231], v[72:75]
	v_mfma_f32_16x16x32_bf16 v[124:127], v[174:177], v[206:209], v[124:127]
	v_mfma_f32_16x16x32_bf16 v[120:123], v[182:185], v[206:209], v[120:123]
	v_mfma_f32_16x16x32_bf16 v[112:115], v[174:177], v[214:217], v[112:115]
	v_mfma_f32_16x16x32_bf16 v[104:107], v[182:185], v[214:217], v[104:107]
	v_mfma_f32_16x16x32_bf16 v[96:99], v[174:177], v[224:227], v[96:99]
	v_mfma_f32_16x16x32_bf16 v[88:91], v[182:185], v[224:227], v[88:91]
	v_mfma_f32_16x16x32_bf16 v[80:83], v[174:177], v[232:235], v[80:83]
	v_mfma_f32_16x16x32_bf16 v[72:75], v[182:185], v[232:235], v[72:75]
	s_setprio 0
	s_setprio 0
	v_mfma_f32_16x16x32_bf16 v[116:119], v[186:189], v[202:205], v[116:119]
	v_mfma_f32_16x16x32_bf16 v[108:111], v[194:197], v[202:205], v[108:111]
	v_mfma_f32_16x16x32_bf16 v[100:103], v[186:189], v[210:213], v[100:103]
	v_mfma_f32_16x16x32_bf16 v[92:95], v[194:197], v[210:213], v[92:95]
	v_mfma_f32_16x16x32_bf16 v[84:87], v[186:189], v[220:223], v[84:87]
	v_mfma_f32_16x16x32_bf16 v[76:79], v[194:197], v[220:223], v[76:79]
	v_mfma_f32_16x16x32_bf16 v[68:71], v[186:189], v[228:231], v[68:71]
	v_mfma_f32_16x16x32_bf16 v[64:67], v[194:197], v[228:231], v[64:67]
	v_mfma_f32_16x16x32_bf16 v[116:119], v[190:193], v[206:209], v[116:119]
	v_mfma_f32_16x16x32_bf16 v[108:111], v[198:201], v[206:209], v[108:111]
	v_mfma_f32_16x16x32_bf16 v[100:103], v[190:193], v[214:217], v[100:103]
	v_mfma_f32_16x16x32_bf16 v[92:95], v[198:201], v[214:217], v[92:95]
	v_mfma_f32_16x16x32_bf16 v[84:87], v[190:193], v[224:227], v[84:87]
	v_mfma_f32_16x16x32_bf16 v[76:79], v[198:201], v[224:227], v[76:79]
	v_mfma_f32_16x16x32_bf16 v[68:71], v[190:193], v[232:235], v[68:71]
	v_mfma_f32_16x16x32_bf16 v[64:67], v[198:201], v[232:235], v[64:67]
	s_setprio 0
	s_barrier
	s_add_i32 s63, s54, s35
	v_lshl_add_u64 v[148:149], s[0:1], 0, v[132:133]
	s_mov_b32 m0, s63
	ds_read_b128 v[202:205], v172 offset:16384
	ds_read_b128 v[206:209], v172 offset:17408
	ds_read_b128 v[210:213], v172 offset:18432
	ds_read_b128 v[214:217], v172 offset:19456
	ds_read_b128 v[220:223], v172 offset:20480
	ds_read_b128 v[224:227], v172 offset:21504
	ds_read_b128 v[228:231], v172 offset:22528
	ds_read_b128 v[232:235], v172 offset:23552
	global_load_lds_dwordx4 v[148:149], off
	s_add_i32 m0, s63, 0x2000
	s_add_u32 s64, s0, 0x80000
	v_lshl_add_u64 v[236:237], s[0:1], 0, v[134:135]
	s_addc_u32 s65, s1, 0
	s_add_i32 s63, s55, s35
	global_load_lds_dwordx4 v[236:237], off
	v_lshl_add_u64 v[238:239], s[64:65], 0, v[132:133]
	s_mov_b32 m0, s63
	v_lshl_add_u64 v[240:241], s[18:19], 0, v[130:131]
	global_load_lds_dwordx4 v[238:239], off
	v_lshl_add_u64 v[238:239], s[64:65], 0, v[134:135]
	s_add_i32 m0, s63, 0x2000
	s_nop 0
	global_load_lds_dwordx4 v[238:239], off
	v_lshl_add_u64 v[238:239], s[18:19], 0, v[128:129]
	s_mov_b32 m0, s47
	s_nop 0
	global_load_lds_dwordx4 v[238:239], off
	s_mov_b32 m0, s48
	s_nop 0
	global_load_lds_dwordx4 v[240:241], off
	s_waitcnt vmcnt(8)
	s_waitcnt lgkmcnt(0)
	s_barrier
; #define PG8_STAGE(bufoff, gbase, voff) do { _Pragma("unroll") for (int _i = 0; _i < 2; ++_i) \
;         __builtin_amdgcn_global_load_lds((const unsigned*)((const char*)(gbase) + (voff)[_i]), (LAS unsigned*)(lds + (bufoff) + ldsw + _i * 8192), 16, 0, 0); } while (0)
; #define PG8_LDA(dst, b, h) do { _Pragma("unroll") for (int m = 0; m < 4; ++m) _Pragma("unroll") for (int k = 0; k < 2; ++k) dst[m][k] = *(const LAS bf16x8*)(lds + PG8_SA(b, h) + aoff + m * 2048 + k * 1024); } while (0)
; #define PG8_LDB(dst, b, h) do { _Pragma("unroll") for (int n = 0; n < 2; ++n) _Pragma("unroll") for (int k = 0; k < 2; ++k) dst[n][k] = *(const LAS bf16x8*)(lds + PG8_SB(b, h) + boff + n * 2048 + k * 1024); } while (0)
; #define PG8_MMA(ai, bj, At, Bt) do { __builtin_amdgcn_s_setprio(1); _Pragma("unroll") for (int m = 0; m < 4; ++m) _Pragma("unroll") for (int n = 0; n < 2; ++n) _Pragma("unroll") for (int k = 0; k < 2; ++k) \
;         acc[ai][bj][m][n] = __builtin_amdgcn_mfma_f32_16x16x32_bf16(Bt[n][k], At[m][k], acc[ai][bj][m][n], 0, 0, 0); __builtin_amdgcn_s_setprio(0); } while (0)
; #define PG8_WAIT_V(n) asm volatile("s_waitcnt vmcnt(" #n ")" ::: "memory")
; #define PG8_WAIT_L(n) asm volatile("s_waitcnt lgkmcnt(" #n ")" ::: "memory")
; #define PG8_BAR __builtin_amdgcn_s_barrier()
; #define PG8_SCHED __builtin_amdgcn_sched_barrier(0)
; template <class Epi, class Sched>
; __device__ __forceinline__ void gemm_phase(LAS unsigned char* lds, const Gemm g, const Sched& S, const Epi& E) {
;     ...
;             PG8_WAIT_V(8); PG8_WAIT_L(0); PG8_BAR; PG8_MMA(1, 0, At, B0); PG8_MMA(1, 1, At, B1); PG8_BAR; PG8_SCHED;
;             PG8_LDB(B0, 1, 0); PG8_LDB(B1, 1, 1); PG8_SCHED; PG8_LDA(At, 1, 0); PG8_STAGE(PG8_SA(0, 1), a2 + hA, voffA);
;             PG8_WAIT_V(8); PG8_WAIT_L(0); PG8_BAR; PG8_MMA(0, 0, At, B0); PG8_MMA(0, 1, At, B1); PG8_BAR; PG8_SCHED;
	s_setprio 0
	s_waitcnt lgkmcnt(0)
	v_mfma_f32_16x16x32_bf16 v[60:63], v[144:147], v[202:205], v[60:63]
	v_mfma_f32_16x16x32_bf16 v[56:59], v[178:181], v[202:205], v[56:59]
	v_mfma_f32_16x16x32_bf16 v[48:51], v[144:147], v[210:213], v[48:51]
	v_mfma_f32_16x16x32_bf16 v[40:43], v[178:181], v[210:213], v[40:43]
	v_mfma_f32_16x16x32_bf16 v[32:35], v[144:147], v[220:223], v[32:35]
	v_mfma_f32_16x16x32_bf16 v[24:27], v[178:181], v[220:223], v[24:27]
	v_mfma_f32_16x16x32_bf16 v[16:19], v[144:147], v[228:231], v[16:19]
	v_mfma_f32_16x16x32_bf16 v[8:11], v[178:181], v[228:231], v[8:11]
	v_mfma_f32_16x16x32_bf16 v[60:63], v[174:177], v[206:209], v[60:63]
	v_mfma_f32_16x16x32_bf16 v[56:59], v[182:185], v[206:209], v[56:59]
	v_mfma_f32_16x16x32_bf16 v[48:51], v[174:177], v[214:217], v[48:51]
	v_mfma_f32_16x16x32_bf16 v[40:43], v[182:185], v[214:217], v[40:43]
	v_mfma_f32_16x16x32_bf16 v[32:35], v[174:177], v[224:227], v[32:35]
	v_mfma_f32_16x16x32_bf16 v[24:27], v[182:185], v[224:227], v[24:27]
	v_mfma_f32_16x16x32_bf16 v[16:19], v[174:177], v[232:235], v[16:19]
	v_mfma_f32_16x16x32_bf16 v[8:11], v[182:185], v[232:235], v[8:11]
	s_setprio 0
	s_setprio 0
	v_mfma_f32_16x16x32_bf16 v[52:55], v[186:189], v[202:205], v[52:55]
	v_mfma_f32_16x16x32_bf16 v[44:47], v[194:197], v[202:205], v[44:47]
	v_mfma_f32_16x16x32_bf16 v[36:39], v[186:189], v[210:213], v[36:39]
	v_mfma_f32_16x16x32_bf16 v[28:31], v[194:197], v[210:213], v[28:31]
	v_mfma_f32_16x16x32_bf16 v[20:23], v[186:189], v[220:223], v[20:23]
	v_mfma_f32_16x16x32_bf16 v[12:15], v[194:197], v[220:223], v[12:15]
	v_mfma_f32_16x16x32_bf16 v[4:7], v[186:189], v[228:231], v[4:7]
	v_mfma_f32_16x16x32_bf16 v[0:3], v[194:197], v[228:231], v[0:3]
	v_mfma_f32_16x16x32_bf16 v[52:55], v[190:193], v[206:209], v[52:55]
	v_mfma_f32_16x16x32_bf16 v[44:47], v[198:201], v[206:209], v[44:47]
	v_mfma_f32_16x16x32_bf16 v[36:39], v[190:193], v[214:217], v[36:39]
	v_mfma_f32_16x16x32_bf16 v[28:31], v[198:201], v[214:217], v[28:31]
	v_mfma_f32_16x16x32_bf16 v[20:23], v[190:193], v[224:227], v[20:23]
	v_mfma_f32_16x16x32_bf16 v[12:15], v[198:201], v[224:227], v[12:15]
	v_mfma_f32_16x16x32_bf16 v[4:7], v[190:193], v[232:235], v[4:7]
	v_mfma_f32_16x16x32_bf16 v[0:3], v[198:201], v[232:235], v[0:3]
	s_setprio 0
	s_barrier
	s_add_i32 s63, 0, 0x18000
	v_add_u32_e32 v173, s63, v168
	s_add_i32 s64, 0, 0x1c000
	ds_read_b128 v[144:147], v173
	ds_read_b128 v[174:177], v173 offset:1024
	ds_read_b128 v[178:181], v173 offset:2048
	ds_read_b128 v[182:185], v173 offset:3072
	v_add_u32_e32 v173, s64, v168
	ds_read_b128 v[186:189], v173
	ds_read_b128 v[190:193], v173 offset:1024
	ds_read_b128 v[194:197], v173 offset:2048
	ds_read_b128 v[198:201], v173 offset:3072
	s_add_u32 s18, s18, 0x1c0000
	s_addc_u32 s19, s19, 0
	s_mov_b32 m0, s49
	v_lshl_add_u64 v[242:243], s[18:19], 0, v[128:129]
	ds_read_b128 v[202:205], v172 offset:32768
	ds_read_b128 v[206:209], v172 offset:33792
	ds_read_b128 v[210:213], v172 offset:34816
	ds_read_b128 v[214:217], v172 offset:35840
	ds_read_b128 v[220:223], v172 offset:36864
	ds_read_b128 v[224:227], v172 offset:37888
	ds_read_b128 v[228:231], v172 offset:38912
	ds_read_b128 v[232:235], v172 offset:39936
	global_load_lds_dwordx4 v[242:243], off
	v_lshl_add_u64 v[242:243], s[18:19], 0, v[130:131]
	s_mov_b32 m0, s50
	s_nop 0
	global_load_lds_dwordx4 v[242:243], off
	s_waitcnt vmcnt(8)
	s_waitcnt lgkmcnt(0)
	s_barrier
	s_setprio 0
	s_waitcnt lgkmcnt(0)
	v_mfma_f32_16x16x32_bf16 v[124:127], v[144:147], v[202:205], v[124:127]
	v_mfma_f32_16x16x32_bf16 v[120:123], v[178:181], v[202:205], v[120:123]
	v_mfma_f32_16x16x32_bf16 v[112:115], v[144:147], v[210:213], v[112:115]
	v_mfma_f32_16x16x32_bf16 v[104:107], v[178:181], v[210:213], v[104:107]
	v_mfma_f32_16x16x32_bf16 v[96:99], v[144:147], v[220:223], v[96:99]
	v_mfma_f32_16x16x32_bf16 v[88:91], v[178:181], v[220:223], v[88:91]
	v_mfma_f32_16x16x32_bf16 v[80:83], v[144:147], v[228:231], v[80:83]
	v_mfma_f32_16x16x32_bf16 v[72:75], v[178:181], v[228:231], v[72:75]
	v_mfma_f32_16x16x32_bf16 v[124:127], v[174:177], v[206:209], v[124:127]
	v_mfma_f32_16x16x32_bf16 v[120:123], v[182:185], v[206:209], v[120:123]
	v_mfma_f32_16x16x32_bf16 v[112:115], v[174:177], v[214:217], v[112:115]
	v_mfma_f32_16x16x32_bf16 v[104:107], v[182:185], v[214:217], v[104:107]
	v_mfma_f32_16x16x32_bf16 v[96:99], v[174:177], v[224:227], v[96:99]
	v_mfma_f32_16x16x32_bf16 v[88:91], v[182:185], v[224:227], v[88:91]
	v_mfma_f32_16x16x32_bf16 v[80:83], v[174:177], v[232:235], v[80:83]
	v_mfma_f32_16x16x32_bf16 v[72:75], v[182:185], v[232:235], v[72:75]
	s_setprio 0
	s_setprio 0
	v_mfma_f32_16x16x32_bf16 v[116:119], v[186:189], v[202:205], v[116:119]
	v_mfma_f32_16x16x32_bf16 v[108:111], v[194:197], v[202:205], v[108:111]
	v_mfma_f32_16x16x32_bf16 v[100:103], v[186:189], v[210:213], v[100:103]
	v_mfma_f32_16x16x32_bf16 v[92:95], v[194:197], v[210:213], v[92:95]
	v_mfma_f32_16x16x32_bf16 v[84:87], v[186:189], v[220:223], v[84:87]
	v_mfma_f32_16x16x32_bf16 v[76:79], v[194:197], v[220:223], v[76:79]
	v_mfma_f32_16x16x32_bf16 v[68:71], v[186:189], v[228:231], v[68:71]
	v_mfma_f32_16x16x32_bf16 v[64:67], v[194:197], v[228:231], v[64:67]
	v_mfma_f32_16x16x32_bf16 v[116:119], v[190:193], v[206:209], v[116:119]
	v_mfma_f32_16x16x32_bf16 v[108:111], v[198:201], v[206:209], v[108:111]
	v_mfma_f32_16x16x32_bf16 v[100:103], v[190:193], v[214:217], v[100:103]
	v_mfma_f32_16x16x32_bf16 v[92:95], v[198:201], v[214:217], v[92:95]
	v_mfma_f32_16x16x32_bf16 v[84:87], v[190:193], v[224:227], v[84:87]
	v_mfma_f32_16x16x32_bf16 v[76:79], v[198:201], v[224:227], v[76:79]
	v_mfma_f32_16x16x32_bf16 v[68:71], v[190:193], v[232:235], v[68:71]
	v_mfma_f32_16x16x32_bf16 v[64:67], v[198:201], v[232:235], v[64:67]
	s_setprio 0
	s_barrier
; #define PG8_STAGE(bufoff, gbase, voff) do { _Pragma("unroll") for (int _i = 0; _i < 2; ++_i) \
;         __builtin_amdgcn_global_load_lds((const unsigned*)((const char*)(gbase) + (voff)[_i]), (LAS unsigned*)(lds + (bufoff) + ldsw + _i * 8192), 16, 0, 0); } while (0)
; #define PG8_LDA(dst, b, h) do { _Pragma("unroll") for (int m = 0; m < 4; ++m) _Pragma("unroll") for (int k = 0; k < 2; ++k) dst[m][k] = *(const LAS bf16x8*)(lds + PG8_SA(b, h) + aoff + m * 2048 + k * 1024); } while (0)
; #define PG8_MMA(ai, bj, At, Bt) do { __builtin_amdgcn_s_setprio(1); _Pragma("unroll") for (int m = 0; m < 4; ++m) _Pragma("unroll") for (int n = 0; n < 2; ++n) _Pragma("unroll") for (int k = 0; k < 2; ++k) \
;         acc[ai][bj][m][n] = __builtin_amdgcn_mfma_f32_16x16x32_bf16(Bt[n][k], At[m][k], acc[ai][bj][m][n], 0, 0, 0); __builtin_amdgcn_s_setprio(0); } while (0)
; #define PG8_WAIT_V(n) asm volatile("s_waitcnt vmcnt(" #n ")" ::: "memory")
; #define PG8_WAIT_L(n) asm volatile("s_waitcnt lgkmcnt(" #n ")" ::: "memory")
; #define PG8_BAR __builtin_amdgcn_s_barrier()
; #define PG8_SCHED __builtin_amdgcn_sched_barrier(0)
; template <class Epi, class Sched>
; __device__ __forceinline__ void gemm_phase(LAS unsigned char* lds, const Gemm g, const Sched& S, const Epi& E) {
;     ...
;             PG8_LDA(At, 1, 1); PG8_STAGE(PG8_SB(1, 0), b3, voffB); PG8_STAGE(PG8_SB(1, 1), b3 + hB, voffB); PG8_STAGE(PG8_SA(1, 0), a3, voffA);
;             PG8_WAIT_V(8); PG8_WAIT_L(0); PG8_BAR; PG8_MMA(1, 0, At, B0); PG8_MMA(1, 1, At, B1); PG8_BAR; PG8_SCHED;
;         }
;         if (wr == 0) PG8_BAR;
	s_add_i32 s18, s63, s35
	v_lshl_add_u64 v[148:149], v[148:149], 0, s[22:23]
	s_mov_b32 m0, s18
	ds_read_b128 v[202:205], v172 offset:49152
	ds_read_b128 v[206:209], v172 offset:50176
	ds_read_b128 v[210:213], v172 offset:51200
	ds_read_b128 v[214:217], v172 offset:52224
	ds_read_b128 v[220:223], v172 offset:53248
	ds_read_b128 v[224:227], v172 offset:54272
	ds_read_b128 v[228:231], v172 offset:55296
	ds_read_b128 v[232:235], v172 offset:56320
	global_load_lds_dwordx4 v[148:149], off
	s_add_i32 m0, s18, 0x2000
	s_add_u32 s0, s0, 0x80080
	v_lshl_add_u64 v[148:149], v[236:237], 0, s[22:23]
	s_addc_u32 s1, s1, 0
	s_add_i32 s18, s64, s35
	global_load_lds_dwordx4 v[148:149], off
	v_lshl_add_u64 v[148:149], s[0:1], 0, v[132:133]
	s_mov_b32 m0, s18
	s_nop 0
	global_load_lds_dwordx4 v[148:149], off
	v_lshl_add_u64 v[148:149], s[0:1], 0, v[134:135]
	s_add_i32 m0, s18, 0x2000
	s_nop 0
	global_load_lds_dwordx4 v[148:149], off
	v_lshl_add_u64 v[148:149], v[238:239], 0, s[22:23]
	s_mov_b32 m0, s51
	s_nop 0
	global_load_lds_dwordx4 v[148:149], off
	v_lshl_add_u64 v[148:149], v[240:241], 0, s[22:23]
	s_mov_b32 m0, s52
	s_nop 0
	global_load_lds_dwordx4 v[148:149], off
	s_waitcnt vmcnt(8)
	s_waitcnt lgkmcnt(0)
	s_barrier
	s_setprio 0
	s_waitcnt lgkmcnt(0)
	v_mfma_f32_16x16x32_bf16 v[60:63], v[144:147], v[202:205], v[60:63]
	v_mfma_f32_16x16x32_bf16 v[56:59], v[178:181], v[202:205], v[56:59]
	v_mfma_f32_16x16x32_bf16 v[48:51], v[144:147], v[210:213], v[48:51]
	v_mfma_f32_16x16x32_bf16 v[40:43], v[178:181], v[210:213], v[40:43]
	v_mfma_f32_16x16x32_bf16 v[32:35], v[144:147], v[220:223], v[32:35]
	v_mfma_f32_16x16x32_bf16 v[24:27], v[178:181], v[220:223], v[24:27]
	v_mfma_f32_16x16x32_bf16 v[16:19], v[144:147], v[228:231], v[16:19]
	v_mfma_f32_16x16x32_bf16 v[8:11], v[178:181], v[228:231], v[8:11]
	v_mfma_f32_16x16x32_bf16 v[60:63], v[174:177], v[206:209], v[60:63]
	v_mfma_f32_16x16x32_bf16 v[56:59], v[182:185], v[206:209], v[56:59]
	v_mfma_f32_16x16x32_bf16 v[48:51], v[174:177], v[214:217], v[48:51]
	v_mfma_f32_16x16x32_bf16 v[40:43], v[182:185], v[214:217], v[40:43]
	v_mfma_f32_16x16x32_bf16 v[32:35], v[174:177], v[224:227], v[32:35]
	v_mfma_f32_16x16x32_bf16 v[24:27], v[182:185], v[224:227], v[24:27]
	v_mfma_f32_16x16x32_bf16 v[16:19], v[174:177], v[232:235], v[16:19]
	v_mfma_f32_16x16x32_bf16 v[8:11], v[182:185], v[232:235], v[8:11]
	s_setprio 0
	s_setprio 0
	v_mfma_f32_16x16x32_bf16 v[52:55], v[186:189], v[202:205], v[52:55]
	v_mfma_f32_16x16x32_bf16 v[44:47], v[194:197], v[202:205], v[44:47]
	v_mfma_f32_16x16x32_bf16 v[36:39], v[186:189], v[210:213], v[36:39]
	v_mfma_f32_16x16x32_bf16 v[28:31], v[194:197], v[210:213], v[28:31]
	v_mfma_f32_16x16x32_bf16 v[20:23], v[186:189], v[220:223], v[20:23]
	v_mfma_f32_16x16x32_bf16 v[12:15], v[194:197], v[220:223], v[12:15]
	v_mfma_f32_16x16x32_bf16 v[4:7], v[186:189], v[228:231], v[4:7]
	v_mfma_f32_16x16x32_bf16 v[0:3], v[194:197], v[228:231], v[0:3]
	v_mfma_f32_16x16x32_bf16 v[52:55], v[190:193], v[206:209], v[52:55]
	v_mfma_f32_16x16x32_bf16 v[44:47], v[198:201], v[206:209], v[44:47]
	v_mfma_f32_16x16x32_bf16 v[36:39], v[190:193], v[214:217], v[36:39]
	v_mfma_f32_16x16x32_bf16 v[28:31], v[198:201], v[214:217], v[28:31]
	v_mfma_f32_16x16x32_bf16 v[20:23], v[190:193], v[224:227], v[20:23]
	v_mfma_f32_16x16x32_bf16 v[12:15], v[198:201], v[224:227], v[12:15]
	v_mfma_f32_16x16x32_bf16 v[4:7], v[190:193], v[232:235], v[4:7]
	v_mfma_f32_16x16x32_bf16 v[0:3], v[198:201], v[232:235], v[0:3]
	s_setprio 0
	s_barrier
	s_add_i32 s62, s62, 2
	s_add_u32 s4, s4, 0x100
	s_addc_u32 s5, s5, 0
	s_add_u32 s42, s42, 0x100
	s_addc_u32 s43, s43, 0
	s_cmp_gt_u32 s62, 29
	s_cbranch_scc0 .LBB0_725
	s_and_b64 vcc, exec, s[26:27]
	s_cbranch_vccz .LBB0_728
	s_barrier

; #define PG8_STAGE(bufoff, gbase, voff) do { _Pragma("unroll") for (int _i = 0; _i < 2; ++_i) \
;         __builtin_amdgcn_global_load_lds((const unsigned*)((const char*)(gbase) + (voff)[_i]), (LAS unsigned*)(lds + (bufoff) + ldsw + _i * 8192), 16, 0, 0); } while (0)
; #define PG8_LDA(dst, b, h) do { _Pragma("unroll") for (int m = 0; m < 4; ++m) _Pragma("unroll") for (int k = 0; k < 2; ++k) dst[m][k] = *(const LAS bf16x8*)(lds + PG8_SA(b, h) + aoff + m * 2048 + k * 1024); } while (0)
; #define PG8_LDB(dst, b, h) do { _Pragma("unroll") for (int n = 0; n < 2; ++n) _Pragma("unroll") for (int k = 0; k < 2; ++k) dst[n][k] = *(const LAS bf16x8*)(lds + PG8_SB(b, h) + boff + n * 2048 + k * 1024); } while (0)
; #define PG8_MMA(ai, bj, At, Bt) do { __builtin_amdgcn_s_setprio(1); _Pragma("unroll") for (int m = 0; m < 4; ++m) _Pragma("unroll") for (int n = 0; n < 2; ++n) _Pragma("unroll") for (int k = 0; k < 2; ++k) \
;         acc[ai][bj][m][n] = __builtin_amdgcn_mfma_f32_16x16x32_bf16(Bt[n][k], At[m][k], acc[ai][bj][m][n], 0, 0, 0); __builtin_amdgcn_s_setprio(0); } while (0)
; #define PG8_WAIT_V(n) asm volatile("s_waitcnt vmcnt(" #n ")" ::: "memory")
; #define PG8_WAIT_L(n) asm volatile("s_waitcnt lgkmcnt(" #n ")" ::: "memory")
; #define PG8_BAR __builtin_amdgcn_s_barrier()
; #define PG8_SCHED __builtin_amdgcn_sched_barrier(0)
; template <class Epi, class Sched>
; __device__ __forceinline__ void gemm_phase(LAS unsigned char* lds, const Gemm g, const Sched& S, const Epi& E) {
;     ...
;             PG8_LDB(B0, 0, 0); PG8_LDB(B1, 0, 1); PG8_SCHED; PG8_LDA(At, 0, 0); PG8_STAGE(PG8_SA(1, 1), a1 + hA, voffA);
;             PG8_WAIT_V(8); PG8_WAIT_L(0); PG8_BAR; PG8_MMA(0, 0, At, B0); PG8_MMA(0, 1, At, B1); PG8_BAR; PG8_SCHED;
;             PG8_LDA(At, 0, 1); PG8_STAGE(PG8_SB(0, 0), b2, voffB); PG8_STAGE(PG8_SB(0, 1), b2 + hB, voffB); PG8_STAGE(PG8_SA(0, 0), a2, voffA);
;             PG8_WAIT_V(8); PG8_WAIT_L(0); PG8_BAR; PG8_MMA(1, 0, At, B0); PG8_MMA(1, 1, At, B1); PG8_BAR; PG8_SCHED;
.LBB0_747:
	ds_read_b128 v[144:147], v153
	ds_read_b128 v[156:159], v153 offset:1024
	ds_read_b128 v[168:171], v153 offset:2048
	ds_read_b128 v[172:175], v153 offset:3072
	ds_read_b128 v[176:179], v154
	ds_read_b128 v[180:183], v154 offset:1024
	ds_read_b128 v[184:187], v154 offset:2048
	ds_read_b128 v[188:191], v154 offset:3072
	s_add_u32 s0, s4, 0xffe40080
	s_addc_u32 s1, s5, -1
	s_cmp_eq_u32 s57, 12
	s_cselect_b32 s19, s29, s1
	s_cselect_b32 s18, s28, s0
	s_cselect_b32 s1, s27, s39
	s_cselect_b32 s0, s56, s38
	v_lshl_add_u64 v[148:149], s[4:5], 0, v[136:137]
	s_add_i32 m0, s42, 0xc000
	ds_read_b128 v[192:195], v155
	ds_read_b128 v[196:199], v155 offset:1024
	ds_read_b128 v[200:203], v155 offset:2048
	ds_read_b128 v[204:207], v155 offset:3072
	ds_read_b128 v[208:211], v155 offset:4096
	ds_read_b128 v[212:215], v155 offset:5120
	ds_read_b128 v[220:223], v155 offset:6144
	ds_read_b128 v[224:227], v155 offset:7168
	global_load_lds_dwordx4 v[148:149], off
	v_lshl_add_u64 v[148:149], s[4:5], 0, v[138:139]
	s_add_i32 m0, s42, 0xe000
	s_nop 0
	global_load_lds_dwordx4 v[148:149], off
	s_waitcnt vmcnt(8)
	s_waitcnt lgkmcnt(0)
	s_barrier
	s_setprio 0
	s_waitcnt lgkmcnt(0)
	v_mfma_f32_16x16x32_bf16 v[124:127], v[144:147], v[192:195], v[124:127]
	v_mfma_f32_16x16x32_bf16 v[120:123], v[168:171], v[192:195], v[120:123]
	v_mfma_f32_16x16x32_bf16 v[108:111], v[144:147], v[200:203], v[108:111]
	v_mfma_f32_16x16x32_bf16 v[104:107], v[168:171], v[200:203], v[104:107]
	v_mfma_f32_16x16x32_bf16 v[92:95], v[144:147], v[208:211], v[92:95]
	v_mfma_f32_16x16x32_bf16 v[88:91], v[168:171], v[208:211], v[88:91]
	v_mfma_f32_16x16x32_bf16 v[76:79], v[144:147], v[220:223], v[76:79]
	v_mfma_f32_16x16x32_bf16 v[72:75], v[168:171], v[220:223], v[72:75]
	v_mfma_f32_16x16x32_bf16 v[124:127], v[156:159], v[196:199], v[124:127]
	v_mfma_f32_16x16x32_bf16 v[120:123], v[172:175], v[196:199], v[120:123]
	v_mfma_f32_16x16x32_bf16 v[108:111], v[156:159], v[204:207], v[108:111]
	v_mfma_f32_16x16x32_bf16 v[104:107], v[172:175], v[204:207], v[104:107]
	v_mfma_f32_16x16x32_bf16 v[92:95], v[156:159], v[212:215], v[92:95]
	v_mfma_f32_16x16x32_bf16 v[88:91], v[172:175], v[212:215], v[88:91]
	v_mfma_f32_16x16x32_bf16 v[76:79], v[156:159], v[224:227], v[76:79]
	v_mfma_f32_16x16x32_bf16 v[72:75], v[172:175], v[224:227], v[72:75]
	s_setprio 0
	s_setprio 0
	v_mfma_f32_16x16x32_bf16 v[116:119], v[176:179], v[192:195], v[116:119]
	v_mfma_f32_16x16x32_bf16 v[112:115], v[184:187], v[192:195], v[112:115]
	v_mfma_f32_16x16x32_bf16 v[100:103], v[176:179], v[200:203], v[100:103]
	v_mfma_f32_16x16x32_bf16 v[96:99], v[184:187], v[200:203], v[96:99]
	v_mfma_f32_16x16x32_bf16 v[84:87], v[176:179], v[208:211], v[84:87]
	v_mfma_f32_16x16x32_bf16 v[80:83], v[184:187], v[208:211], v[80:83]
	v_mfma_f32_16x16x32_bf16 v[68:71], v[176:179], v[220:223], v[68:71]
	v_mfma_f32_16x16x32_bf16 v[64:67], v[184:187], v[220:223], v[64:67]
	v_mfma_f32_16x16x32_bf16 v[116:119], v[180:183], v[196:199], v[116:119]
	v_mfma_f32_16x16x32_bf16 v[112:115], v[188:191], v[196:199], v[112:115]
	v_mfma_f32_16x16x32_bf16 v[100:103], v[180:183], v[204:207], v[100:103]
	v_mfma_f32_16x16x32_bf16 v[96:99], v[188:191], v[204:207], v[96:99]
	v_mfma_f32_16x16x32_bf16 v[84:87], v[180:183], v[212:215], v[84:87]
	v_mfma_f32_16x16x32_bf16 v[80:83], v[188:191], v[212:215], v[80:83]
	v_mfma_f32_16x16x32_bf16 v[68:71], v[180:183], v[224:227], v[68:71]
	v_mfma_f32_16x16x32_bf16 v[64:67], v[188:191], v[224:227], v[64:67]
	s_setprio 0
	s_barrier
	s_add_i32 s58, s50, s35
	v_lshl_add_u64 v[148:149], s[0:1], 0, v[132:133]
	s_mov_b32 m0, s58
	ds_read_b128 v[192:195], v155 offset:16384
	ds_read_b128 v[196:199], v155 offset:17408
	ds_read_b128 v[200:203], v155 offset:18432
	ds_read_b128 v[204:207], v155 offset:19456
	ds_read_b128 v[208:211], v155 offset:20480
	ds_read_b128 v[212:215], v155 offset:21504
	ds_read_b128 v[220:223], v155 offset:22528
	ds_read_b128 v[224:227], v155 offset:23552
	global_load_lds_dwordx4 v[148:149], off
	s_add_i32 m0, s58, 0x2000
	s_add_u32 s58, s0, 0x40000
	v_lshl_add_u64 v[160:161], s[0:1], 0, v[134:135]
	s_addc_u32 s59, s1, 0
	s_add_i32 s60, s51, s35
	global_load_lds_dwordx4 v[160:161], off
	v_lshl_add_u64 v[216:217], s[58:59], 0, v[132:133]
	s_mov_b32 m0, s60
	v_lshl_add_u64 v[228:229], s[18:19], 0, v[130:131]
	global_load_lds_dwordx4 v[216:217], off
	v_lshl_add_u64 v[216:217], s[58:59], 0, v[134:135]
	s_add_i32 m0, s60, 0x2000
	s_nop 0
	global_load_lds_dwordx4 v[216:217], off
	v_lshl_add_u64 v[216:217], s[18:19], 0, v[128:129]
	s_mov_b32 m0, s42
	s_nop 0
	global_load_lds_dwordx4 v[216:217], off
	s_mov_b32 m0, s43
	s_nop 0
	global_load_lds_dwordx4 v[228:229], off
	s_waitcnt vmcnt(8)
	s_waitcnt lgkmcnt(0)
	s_barrier
; #define PG8_STAGE(bufoff, gbase, voff) do { _Pragma("unroll") for (int _i = 0; _i < 2; ++_i) \
;         __builtin_amdgcn_global_load_lds((const unsigned*)((const char*)(gbase) + (voff)[_i]), (LAS unsigned*)(lds + (bufoff) + ldsw + _i * 8192), 16, 0, 0); } while (0)
; #define PG8_LDA(dst, b, h) do { _Pragma("unroll") for (int m = 0; m < 4; ++m) _Pragma("unroll") for (int k = 0; k < 2; ++k) dst[m][k] = *(const LAS bf16x8*)(lds + PG8_SA(b, h) + aoff + m * 2048 + k * 1024); } while (0)
; #define PG8_LDB(dst, b, h) do { _Pragma("unroll") for (int n = 0; n < 2; ++n) _Pragma("unroll") for (int k = 0; k < 2; ++k) dst[n][k] = *(const LAS bf16x8*)(lds + PG8_SB(b, h) + boff + n * 2048 + k * 1024); } while (0)
; #define PG8_MMA(ai, bj, At, Bt) do { __builtin_amdgcn_s_setprio(1); _Pragma("unroll") for (int m = 0; m < 4; ++m) _Pragma("unroll") for (int n = 0; n < 2; ++n) _Pragma("unroll") for (int k = 0; k < 2; ++k) \
;         acc[ai][bj][m][n] = __builtin_amdgcn_mfma_f32_16x16x32_bf16(Bt[n][k], At[m][k], acc[ai][bj][m][n], 0, 0, 0); __builtin_amdgcn_s_setprio(0); } while (0)
; #define PG8_WAIT_V(n) asm volatile("s_waitcnt vmcnt(" #n ")" ::: "memory")
; #define PG8_WAIT_L(n) asm volatile("s_waitcnt lgkmcnt(" #n ")" ::: "memory")
; #define PG8_BAR __builtin_amdgcn_s_barrier()
; #define PG8_SCHED __builtin_amdgcn_sched_barrier(0)
; template <class Epi, class Sched>
; __device__ __forceinline__ void gemm_phase(LAS unsigned char* lds, const Gemm g, const Sched& S, const Epi& E) {
;     ...
;             PG8_WAIT_V(8); PG8_WAIT_L(0); PG8_BAR; PG8_MMA(1, 0, At, B0); PG8_MMA(1, 1, At, B1); PG8_BAR; PG8_SCHED;
;             PG8_LDB(B0, 1, 0); PG8_LDB(B1, 1, 1); PG8_SCHED; PG8_LDA(At, 1, 0); PG8_STAGE(PG8_SA(0, 1), a2 + hA, voffA);
;             PG8_WAIT_V(8); PG8_WAIT_L(0); PG8_BAR; PG8_MMA(0, 0, At, B0); PG8_MMA(0, 1, At, B1); PG8_BAR; PG8_SCHED;
	s_setprio 0
	s_waitcnt lgkmcnt(0)
	v_mfma_f32_16x16x32_bf16 v[60:63], v[144:147], v[192:195], v[60:63]
	v_mfma_f32_16x16x32_bf16 v[56:59], v[168:171], v[192:195], v[56:59]
	v_mfma_f32_16x16x32_bf16 v[44:47], v[144:147], v[200:203], v[44:47]
	v_mfma_f32_16x16x32_bf16 v[40:43], v[168:171], v[200:203], v[40:43]
	v_mfma_f32_16x16x32_bf16 v[28:31], v[144:147], v[208:211], v[28:31]
	v_mfma_f32_16x16x32_bf16 v[24:27], v[168:171], v[208:211], v[24:27]
	v_mfma_f32_16x16x32_bf16 v[12:15], v[144:147], v[220:223], v[12:15]
	v_mfma_f32_16x16x32_bf16 v[8:11], v[168:171], v[220:223], v[8:11]
	v_mfma_f32_16x16x32_bf16 v[60:63], v[156:159], v[196:199], v[60:63]
	v_mfma_f32_16x16x32_bf16 v[56:59], v[172:175], v[196:199], v[56:59]
	v_mfma_f32_16x16x32_bf16 v[44:47], v[156:159], v[204:207], v[44:47]
	v_mfma_f32_16x16x32_bf16 v[40:43], v[172:175], v[204:207], v[40:43]
	v_mfma_f32_16x16x32_bf16 v[28:31], v[156:159], v[212:215], v[28:31]
	v_mfma_f32_16x16x32_bf16 v[24:27], v[172:175], v[212:215], v[24:27]
	v_mfma_f32_16x16x32_bf16 v[12:15], v[156:159], v[224:227], v[12:15]
	v_mfma_f32_16x16x32_bf16 v[8:11], v[172:175], v[224:227], v[8:11]
	s_setprio 0
	s_setprio 0
	v_mfma_f32_16x16x32_bf16 v[52:55], v[176:179], v[192:195], v[52:55]
	v_mfma_f32_16x16x32_bf16 v[48:51], v[184:187], v[192:195], v[48:51]
	v_mfma_f32_16x16x32_bf16 v[36:39], v[176:179], v[200:203], v[36:39]
	v_mfma_f32_16x16x32_bf16 v[32:35], v[184:187], v[200:203], v[32:35]
	v_mfma_f32_16x16x32_bf16 v[20:23], v[176:179], v[208:211], v[20:23]
	v_mfma_f32_16x16x32_bf16 v[16:19], v[184:187], v[208:211], v[16:19]
	v_mfma_f32_16x16x32_bf16 v[4:7], v[176:179], v[220:223], v[4:7]
	v_mfma_f32_16x16x32_bf16 v[0:3], v[184:187], v[220:223], v[0:3]
	v_mfma_f32_16x16x32_bf16 v[52:55], v[180:183], v[196:199], v[52:55]
	v_mfma_f32_16x16x32_bf16 v[48:51], v[188:191], v[196:199], v[48:51]
	v_mfma_f32_16x16x32_bf16 v[36:39], v[180:183], v[204:207], v[36:39]
	v_mfma_f32_16x16x32_bf16 v[32:35], v[188:191], v[204:207], v[32:35]
	v_mfma_f32_16x16x32_bf16 v[20:23], v[180:183], v[212:215], v[20:23]
	v_mfma_f32_16x16x32_bf16 v[16:19], v[188:191], v[212:215], v[16:19]
	v_mfma_f32_16x16x32_bf16 v[4:7], v[180:183], v[224:227], v[4:7]
	v_mfma_f32_16x16x32_bf16 v[0:3], v[188:191], v[224:227], v[0:3]
	s_setprio 0
	s_barrier
	s_add_i32 s58, 0, 0x18000
	s_add_i32 s59, 0, 0x1c000
	v_add_u32_e32 v172, s58, v151
	v_add_u32_e32 v188, s59, v151
	ds_read_b128 v[144:147], v172
	ds_read_b128 v[156:159], v172 offset:1024
	ds_read_b128 v[168:171], v172 offset:2048
	ds_read_b128 v[172:175], v172 offset:3072
	ds_read_b128 v[176:179], v188
	ds_read_b128 v[180:183], v188 offset:1024
	ds_read_b128 v[184:187], v188 offset:2048
	ds_read_b128 v[188:191], v188 offset:3072
	s_add_u32 s18, s18, 0x1c0000
	s_addc_u32 s19, s19, 0
	s_mov_b32 m0, s44
	v_lshl_add_u64 v[230:231], s[18:19], 0, v[128:129]
	ds_read_b128 v[192:195], v155 offset:32768
	ds_read_b128 v[196:199], v155 offset:33792
	ds_read_b128 v[200:203], v155 offset:34816
	ds_read_b128 v[204:207], v155 offset:35840
	ds_read_b128 v[208:211], v155 offset:36864
	ds_read_b128 v[212:215], v155 offset:37888
	ds_read_b128 v[220:223], v155 offset:38912
	ds_read_b128 v[224:227], v155 offset:39936
	global_load_lds_dwordx4 v[230:231], off
	v_lshl_add_u64 v[230:231], s[18:19], 0, v[130:131]
	s_mov_b32 m0, s45
	s_nop 0
	global_load_lds_dwordx4 v[230:231], off
	s_waitcnt vmcnt(8)
	s_waitcnt lgkmcnt(0)
	s_barrier
	s_setprio 0
	s_waitcnt lgkmcnt(0)
	v_mfma_f32_16x16x32_bf16 v[124:127], v[144:147], v[192:195], v[124:127]
	v_mfma_f32_16x16x32_bf16 v[120:123], v[168:171], v[192:195], v[120:123]
	v_mfma_f32_16x16x32_bf16 v[108:111], v[144:147], v[200:203], v[108:111]
	v_mfma_f32_16x16x32_bf16 v[104:107], v[168:171], v[200:203], v[104:107]
	v_mfma_f32_16x16x32_bf16 v[92:95], v[144:147], v[208:211], v[92:95]
	v_mfma_f32_16x16x32_bf16 v[88:91], v[168:171], v[208:211], v[88:91]
	v_mfma_f32_16x16x32_bf16 v[76:79], v[144:147], v[220:223], v[76:79]
	v_mfma_f32_16x16x32_bf16 v[72:75], v[168:171], v[220:223], v[72:75]
	v_mfma_f32_16x16x32_bf16 v[124:127], v[156:159], v[196:199], v[124:127]
	v_mfma_f32_16x16x32_bf16 v[120:123], v[172:175], v[196:199], v[120:123]
	v_mfma_f32_16x16x32_bf16 v[108:111], v[156:159], v[204:207], v[108:111]
	v_mfma_f32_16x16x32_bf16 v[104:107], v[172:175], v[204:207], v[104:107]
	v_mfma_f32_16x16x32_bf16 v[92:95], v[156:159], v[212:215], v[92:95]
	v_mfma_f32_16x16x32_bf16 v[88:91], v[172:175], v[212:215], v[88:91]
	v_mfma_f32_16x16x32_bf16 v[76:79], v[156:159], v[224:227], v[76:79]
	v_mfma_f32_16x16x32_bf16 v[72:75], v[172:175], v[224:227], v[72:75]
	s_setprio 0
	s_setprio 0
	v_mfma_f32_16x16x32_bf16 v[116:119], v[176:179], v[192:195], v[116:119]
	v_mfma_f32_16x16x32_bf16 v[112:115], v[184:187], v[192:195], v[112:115]
	v_mfma_f32_16x16x32_bf16 v[100:103], v[176:179], v[200:203], v[100:103]
	v_mfma_f32_16x16x32_bf16 v[96:99], v[184:187], v[200:203], v[96:99]
	v_mfma_f32_16x16x32_bf16 v[84:87], v[176:179], v[208:211], v[84:87]
	v_mfma_f32_16x16x32_bf16 v[80:83], v[184:187], v[208:211], v[80:83]
	v_mfma_f32_16x16x32_bf16 v[68:71], v[176:179], v[220:223], v[68:71]
	v_mfma_f32_16x16x32_bf16 v[64:67], v[184:187], v[220:223], v[64:67]
	v_mfma_f32_16x16x32_bf16 v[116:119], v[180:183], v[196:199], v[116:119]
	v_mfma_f32_16x16x32_bf16 v[112:115], v[188:191], v[196:199], v[112:115]
	v_mfma_f32_16x16x32_bf16 v[100:103], v[180:183], v[204:207], v[100:103]
	v_mfma_f32_16x16x32_bf16 v[96:99], v[188:191], v[204:207], v[96:99]
	v_mfma_f32_16x16x32_bf16 v[84:87], v[180:183], v[212:215], v[84:87]
	v_mfma_f32_16x16x32_bf16 v[80:83], v[188:191], v[212:215], v[80:83]
	v_mfma_f32_16x16x32_bf16 v[68:71], v[180:183], v[224:227], v[68:71]
	v_mfma_f32_16x16x32_bf16 v[64:67], v[188:191], v[224:227], v[64:67]
	s_setprio 0
	s_barrier
; #define PG8_STAGE(bufoff, gbase, voff) do { _Pragma("unroll") for (int _i = 0; _i < 2; ++_i) \
;         __builtin_amdgcn_global_load_lds((const unsigned*)((const char*)(gbase) + (voff)[_i]), (LAS unsigned*)(lds + (bufoff) + ldsw + _i * 8192), 16, 0, 0); } while (0)
; #define PG8_LDA(dst, b, h) do { _Pragma("unroll") for (int m = 0; m < 4; ++m) _Pragma("unroll") for (int k = 0; k < 2; ++k) dst[m][k] = *(const LAS bf16x8*)(lds + PG8_SA(b, h) + aoff + m * 2048 + k * 1024); } while (0)
; #define PG8_MMA(ai, bj, At, Bt) do { __builtin_amdgcn_s_setprio(1); _Pragma("unroll") for (int m = 0; m < 4; ++m) _Pragma("unroll") for (int n = 0; n < 2; ++n) _Pragma("unroll") for (int k = 0; k < 2; ++k) \
;         acc[ai][bj][m][n] = __builtin_amdgcn_mfma_f32_16x16x32_bf16(Bt[n][k], At[m][k], acc[ai][bj][m][n], 0, 0, 0); __builtin_amdgcn_s_setprio(0); } while (0)
; #define PG8_WAIT_V(n) asm volatile("s_waitcnt vmcnt(" #n ")" ::: "memory")
; #define PG8_WAIT_L(n) asm volatile("s_waitcnt lgkmcnt(" #n ")" ::: "memory")
; #define PG8_BAR __builtin_amdgcn_s_barrier()
; #define PG8_SCHED __builtin_amdgcn_sched_barrier(0)
; template <class Epi, class Sched>
; __device__ __forceinline__ void gemm_phase(LAS unsigned char* lds, const Gemm g, const Sched& S, const Epi& E) {
;     ...
;             PG8_LDA(At, 1, 1); PG8_STAGE(PG8_SB(1, 0), b3, voffB); PG8_STAGE(PG8_SB(1, 1), b3 + hB, voffB); PG8_STAGE(PG8_SA(1, 0), a3, voffA);
;             PG8_WAIT_V(8); PG8_WAIT_L(0); PG8_BAR; PG8_MMA(1, 0, At, B0); PG8_MMA(1, 1, At, B1); PG8_BAR; PG8_SCHED;
;         }
;         if (wr == 0) PG8_BAR;
	s_add_i32 s18, s58, s35
	v_lshl_add_u64 v[148:149], v[148:149], 0, s[16:17]
	s_mov_b32 m0, s18
	ds_read_b128 v[192:195], v155 offset:49152
	ds_read_b128 v[196:199], v155 offset:50176
	ds_read_b128 v[200:203], v155 offset:51200
	ds_read_b128 v[204:207], v155 offset:52224
	ds_read_b128 v[208:211], v155 offset:53248
	ds_read_b128 v[212:215], v155 offset:54272
	ds_read_b128 v[220:223], v155 offset:55296
	ds_read_b128 v[224:227], v155 offset:56320
	global_load_lds_dwordx4 v[148:149], off
	s_add_i32 m0, s18, 0x2000
	s_add_u32 s0, s0, 0x40080
	v_lshl_add_u64 v[148:149], v[160:161], 0, s[16:17]
	s_addc_u32 s1, s1, 0
	s_add_i32 s18, s59, s35
	global_load_lds_dwordx4 v[148:149], off
	v_lshl_add_u64 v[148:149], s[0:1], 0, v[132:133]
	s_mov_b32 m0, s18
	s_nop 0
	global_load_lds_dwordx4 v[148:149], off
	v_lshl_add_u64 v[148:149], s[0:1], 0, v[134:135]
	s_add_i32 m0, s18, 0x2000
	s_nop 0
	global_load_lds_dwordx4 v[148:149], off
	v_lshl_add_u64 v[148:149], v[216:217], 0, s[16:17]
	s_mov_b32 m0, s48
	s_nop 0
	global_load_lds_dwordx4 v[148:149], off
	v_lshl_add_u64 v[148:149], v[228:229], 0, s[16:17]
	s_mov_b32 m0, s49
	s_nop 0
	global_load_lds_dwordx4 v[148:149], off
	s_waitcnt vmcnt(8)
	s_waitcnt lgkmcnt(0)
	s_barrier
	s_setprio 0
	s_waitcnt lgkmcnt(0)
	v_mfma_f32_16x16x32_bf16 v[60:63], v[144:147], v[192:195], v[60:63]
	v_mfma_f32_16x16x32_bf16 v[56:59], v[168:171], v[192:195], v[56:59]
	v_mfma_f32_16x16x32_bf16 v[44:47], v[144:147], v[200:203], v[44:47]
	v_mfma_f32_16x16x32_bf16 v[40:43], v[168:171], v[200:203], v[40:43]
	v_mfma_f32_16x16x32_bf16 v[28:31], v[144:147], v[208:211], v[28:31]
	v_mfma_f32_16x16x32_bf16 v[24:27], v[168:171], v[208:211], v[24:27]
	v_mfma_f32_16x16x32_bf16 v[12:15], v[144:147], v[220:223], v[12:15]
	v_mfma_f32_16x16x32_bf16 v[8:11], v[168:171], v[220:223], v[8:11]
	v_mfma_f32_16x16x32_bf16 v[60:63], v[156:159], v[196:199], v[60:63]
	v_mfma_f32_16x16x32_bf16 v[56:59], v[172:175], v[196:199], v[56:59]
	v_mfma_f32_16x16x32_bf16 v[44:47], v[156:159], v[204:207], v[44:47]
	v_mfma_f32_16x16x32_bf16 v[40:43], v[172:175], v[204:207], v[40:43]
	v_mfma_f32_16x16x32_bf16 v[28:31], v[156:159], v[212:215], v[28:31]
	v_mfma_f32_16x16x32_bf16 v[24:27], v[172:175], v[212:215], v[24:27]
	v_mfma_f32_16x16x32_bf16 v[12:15], v[156:159], v[224:227], v[12:15]
	v_mfma_f32_16x16x32_bf16 v[8:11], v[172:175], v[224:227], v[8:11]
	s_setprio 0
	s_setprio 0
	v_mfma_f32_16x16x32_bf16 v[52:55], v[176:179], v[192:195], v[52:55]
	v_mfma_f32_16x16x32_bf16 v[48:51], v[184:187], v[192:195], v[48:51]
	v_mfma_f32_16x16x32_bf16 v[36:39], v[176:179], v[200:203], v[36:39]
	v_mfma_f32_16x16x32_bf16 v[32:35], v[184:187], v[200:203], v[32:35]
	v_mfma_f32_16x16x32_bf16 v[20:23], v[176:179], v[208:211], v[20:23]
	v_mfma_f32_16x16x32_bf16 v[16:19], v[184:187], v[208:211], v[16:19]
	v_mfma_f32_16x16x32_bf16 v[4:7], v[176:179], v[220:223], v[4:7]
	v_mfma_f32_16x16x32_bf16 v[0:3], v[184:187], v[220:223], v[0:3]
	v_mfma_f32_16x16x32_bf16 v[52:55], v[180:183], v[196:199], v[52:55]
	v_mfma_f32_16x16x32_bf16 v[48:51], v[188:191], v[196:199], v[48:51]
	v_mfma_f32_16x16x32_bf16 v[36:39], v[180:183], v[204:207], v[36:39]
	v_mfma_f32_16x16x32_bf16 v[32:35], v[188:191], v[204:207], v[32:35]
	v_mfma_f32_16x16x32_bf16 v[20:23], v[180:183], v[212:215], v[20:23]
	v_mfma_f32_16x16x32_bf16 v[16:19], v[188:191], v[212:215], v[16:19]
	v_mfma_f32_16x16x32_bf16 v[4:7], v[180:183], v[224:227], v[4:7]
	v_mfma_f32_16x16x32_bf16 v[0:3], v[188:191], v[224:227], v[0:3]
	s_setprio 0
	s_barrier
	s_add_i32 s57, s57, 2
	s_add_u32 s4, s4, 0x100
	s_addc_u32 s5, s5, 0
	s_add_u32 s38, s38, 0x100
	s_addc_u32 s39, s39, 0
	s_cmp_gt_u32 s57, 13
	s_cbranch_scc0 .LBB0_747
	s_and_b64 vcc, exec, s[20:21]
	s_cbranch_vccz .LBB0_750
	s_barrier

; #define PG8_STAGE(bufoff, gbase, voff) do { _Pragma("unroll") for (int _i = 0; _i < 2; ++_i) \
;         __builtin_amdgcn_global_load_lds((const unsigned*)((const char*)(gbase) + (voff)[_i]), (LAS unsigned*)(lds + (bufoff) + ldsw + _i * 8192), 16, 0, 0); } while (0)
; #define PG8_LDA(dst, b, h) do { _Pragma("unroll") for (int m = 0; m < 4; ++m) _Pragma("unroll") for (int k = 0; k < 2; ++k) dst[m][k] = *(const LAS bf16x8*)(lds + PG8_SA(b, h) + aoff + m * 2048 + k * 1024); } while (0)
; #define PG8_LDB(dst, b, h) do { _Pragma("unroll") for (int n = 0; n < 2; ++n) _Pragma("unroll") for (int k = 0; k < 2; ++k) dst[n][k] = *(const LAS bf16x8*)(lds + PG8_SB(b, h) + boff + n * 2048 + k * 1024); } while (0)
; #define PG8_MMA(ai, bj, At, Bt) do { __builtin_amdgcn_s_setprio(1); _Pragma("unroll") for (int m = 0; m < 4; ++m) _Pragma("unroll") for (int n = 0; n < 2; ++n) _Pragma("unroll") for (int k = 0; k < 2; ++k) \
;         acc[ai][bj][m][n] = __builtin_amdgcn_mfma_f32_16x16x32_bf16(Bt[n][k], At[m][k], acc[ai][bj][m][n], 0, 0, 0); __builtin_amdgcn_s_setprio(0); } while (0)
; #define PG8_WAIT_V(n) asm volatile("s_waitcnt vmcnt(" #n ")" ::: "memory")
; #define PG8_WAIT_L(n) asm volatile("s_waitcnt lgkmcnt(" #n ")" ::: "memory")
; #define PG8_BAR __builtin_amdgcn_s_barrier()
; #define PG8_SCHED __builtin_amdgcn_sched_barrier(0)
; template <class Epi, class Sched>
; __device__ __forceinline__ void gemm_phase(LAS unsigned char* lds, const Gemm g, const Sched& S, const Epi& E) {
;     ...
;             PG8_LDB(B0, 0, 0); PG8_LDB(B1, 0, 1); PG8_SCHED; PG8_LDA(At, 0, 0); PG8_STAGE(PG8_SA(1, 1), a1 + hA, voffA);
;             PG8_WAIT_V(8); PG8_WAIT_L(0); PG8_BAR; PG8_MMA(0, 0, At, B0); PG8_MMA(0, 1, At, B1); PG8_BAR; PG8_SCHED;
;             PG8_LDA(At, 0, 1); PG8_STAGE(PG8_SB(0, 0), b2, voffB); PG8_STAGE(PG8_SB(0, 1), b2 + hB, voffB); PG8_STAGE(PG8_SA(0, 0), a2, voffA);
;             PG8_WAIT_V(8); PG8_WAIT_L(0); PG8_BAR; PG8_MMA(1, 0, At, B0); PG8_MMA(1, 1, At, B1); PG8_BAR; PG8_SCHED;
.LBB0_822:
	ds_read_b128 v[128:131], v171
	ds_read_b128 v[132:135], v171 offset:1024
	ds_read_b128 v[136:139], v171 offset:2048
	ds_read_b128 v[140:143], v171 offset:3072
	ds_read_b128 v[174:177], v172
	ds_read_b128 v[178:181], v172 offset:1024
	ds_read_b128 v[182:185], v172 offset:2048
	ds_read_b128 v[186:189], v172 offset:3072
	s_add_u32 s0, s46, 0xfff80080
	s_addc_u32 s1, s47, -1
	s_cmp_eq_u32 s63, 28
	s_cselect_b32 s19, s39, s1
	s_cselect_b32 s18, s61, s0
	s_cselect_b32 s1, s31, s49
	s_cselect_b32 s0, s62, s48
	v_lshl_add_u64 v[160:161], s[46:47], 0, v[152:153]
	s_add_i32 m0, s35, 0xc000
	ds_read_b128 v[190:193], v173
	ds_read_b128 v[194:197], v173 offset:1024
	ds_read_b128 v[198:201], v173 offset:2048
	ds_read_b128 v[202:205], v173 offset:3072
	ds_read_b128 v[206:209], v173 offset:4096
	ds_read_b128 v[210:213], v173 offset:5120
	ds_read_b128 v[214:217], v173 offset:6144
	ds_read_b128 v[220:223], v173 offset:7168
	global_load_lds_dwordx4 v[160:161], off
	v_lshl_add_u64 v[160:161], s[46:47], 0, v[154:155]
	s_add_i32 m0, s35, 0xe000
	s_nop 0
	global_load_lds_dwordx4 v[160:161], off
	s_waitcnt vmcnt(8)
	s_waitcnt lgkmcnt(0)
	s_barrier
	s_setprio 0
	s_waitcnt lgkmcnt(0)
	v_mfma_f32_16x16x32_bf16 v[124:127], v[128:131], v[190:193], v[124:127]
	v_mfma_f32_16x16x32_bf16 v[120:123], v[136:139], v[190:193], v[120:123]
	v_mfma_f32_16x16x32_bf16 v[116:119], v[128:131], v[198:201], v[116:119]
	v_mfma_f32_16x16x32_bf16 v[104:107], v[136:139], v[198:201], v[104:107]
	v_mfma_f32_16x16x32_bf16 v[100:103], v[128:131], v[206:209], v[100:103]
	v_mfma_f32_16x16x32_bf16 v[88:91], v[136:139], v[206:209], v[88:91]
	v_mfma_f32_16x16x32_bf16 v[84:87], v[128:131], v[214:217], v[84:87]
	v_mfma_f32_16x16x32_bf16 v[72:75], v[136:139], v[214:217], v[72:75]
	v_mfma_f32_16x16x32_bf16 v[124:127], v[132:135], v[194:197], v[124:127]
	v_mfma_f32_16x16x32_bf16 v[120:123], v[140:143], v[194:197], v[120:123]
	v_mfma_f32_16x16x32_bf16 v[116:119], v[132:135], v[202:205], v[116:119]
	v_mfma_f32_16x16x32_bf16 v[104:107], v[140:143], v[202:205], v[104:107]
	v_mfma_f32_16x16x32_bf16 v[100:103], v[132:135], v[210:213], v[100:103]
	v_mfma_f32_16x16x32_bf16 v[88:91], v[140:143], v[210:213], v[88:91]
	v_mfma_f32_16x16x32_bf16 v[84:87], v[132:135], v[220:223], v[84:87]
	v_mfma_f32_16x16x32_bf16 v[72:75], v[140:143], v[220:223], v[72:75]
	s_setprio 0
	s_setprio 0
	v_mfma_f32_16x16x32_bf16 v[112:115], v[174:177], v[190:193], v[112:115]
	v_mfma_f32_16x16x32_bf16 v[108:111], v[182:185], v[190:193], v[108:111]
	v_mfma_f32_16x16x32_bf16 v[96:99], v[174:177], v[198:201], v[96:99]
	v_mfma_f32_16x16x32_bf16 v[92:95], v[182:185], v[198:201], v[92:95]
	v_mfma_f32_16x16x32_bf16 v[80:83], v[174:177], v[206:209], v[80:83]
	v_mfma_f32_16x16x32_bf16 v[76:79], v[182:185], v[206:209], v[76:79]
	v_mfma_f32_16x16x32_bf16 v[68:71], v[174:177], v[214:217], v[68:71]
	v_mfma_f32_16x16x32_bf16 v[64:67], v[182:185], v[214:217], v[64:67]
	v_mfma_f32_16x16x32_bf16 v[112:115], v[178:181], v[194:197], v[112:115]
	v_mfma_f32_16x16x32_bf16 v[108:111], v[186:189], v[194:197], v[108:111]
	v_mfma_f32_16x16x32_bf16 v[96:99], v[178:181], v[202:205], v[96:99]
	v_mfma_f32_16x16x32_bf16 v[92:95], v[186:189], v[202:205], v[92:95]
	v_mfma_f32_16x16x32_bf16 v[80:83], v[178:181], v[210:213], v[80:83]
	v_mfma_f32_16x16x32_bf16 v[76:79], v[186:189], v[210:213], v[76:79]
	v_mfma_f32_16x16x32_bf16 v[68:71], v[178:181], v[220:223], v[68:71]
	v_mfma_f32_16x16x32_bf16 v[64:67], v[186:189], v[220:223], v[64:67]
	s_setprio 0
	s_barrier
	s_add_i32 s64, s58, s33
	v_lshl_add_u64 v[160:161], s[0:1], 0, v[146:147]
	s_mov_b32 m0, s64
	ds_read_b128 v[190:193], v173 offset:16384
	ds_read_b128 v[194:197], v173 offset:17408
	ds_read_b128 v[198:201], v173 offset:18432
	ds_read_b128 v[202:205], v173 offset:19456
	ds_read_b128 v[206:209], v173 offset:20480
	ds_read_b128 v[210:213], v173 offset:21504
	ds_read_b128 v[214:217], v173 offset:22528
	ds_read_b128 v[220:223], v173 offset:23552
	global_load_lds_dwordx4 v[160:161], off
	s_add_i32 m0, s64, 0x2000
	s_add_u32 s64, s0, 0x80000
	v_lshl_add_u64 v[224:225], s[0:1], 0, v[150:151]
	s_addc_u32 s65, s1, 0
	s_add_i32 s66, s59, s33
	global_load_lds_dwordx4 v[224:225], off
	v_lshl_add_u64 v[226:227], s[64:65], 0, v[146:147]
	s_mov_b32 m0, s66
	v_lshl_add_u64 v[228:229], s[18:19], 0, v[148:149]
	global_load_lds_dwordx4 v[226:227], off
	v_lshl_add_u64 v[226:227], s[64:65], 0, v[150:151]
	s_add_i32 m0, s66, 0x2000
	s_nop 0
	global_load_lds_dwordx4 v[226:227], off
	v_lshl_add_u64 v[226:227], s[18:19], 0, v[144:145]
	s_mov_b32 m0, s35
	s_nop 0
	global_load_lds_dwordx4 v[226:227], off
	s_mov_b32 m0, s45
	s_nop 0
	global_load_lds_dwordx4 v[228:229], off
	s_waitcnt vmcnt(8)
	s_waitcnt lgkmcnt(0)
	s_barrier
; #define PG8_STAGE(bufoff, gbase, voff) do { _Pragma("unroll") for (int _i = 0; _i < 2; ++_i) \
;         __builtin_amdgcn_global_load_lds((const unsigned*)((const char*)(gbase) + (voff)[_i]), (LAS unsigned*)(lds + (bufoff) + ldsw + _i * 8192), 16, 0, 0); } while (0)
; #define PG8_LDA(dst, b, h) do { _Pragma("unroll") for (int m = 0; m < 4; ++m) _Pragma("unroll") for (int k = 0; k < 2; ++k) dst[m][k] = *(const LAS bf16x8*)(lds + PG8_SA(b, h) + aoff + m * 2048 + k * 1024); } while (0)
; #define PG8_LDB(dst, b, h) do { _Pragma("unroll") for (int n = 0; n < 2; ++n) _Pragma("unroll") for (int k = 0; k < 2; ++k) dst[n][k] = *(const LAS bf16x8*)(lds + PG8_SB(b, h) + boff + n * 2048 + k * 1024); } while (0)
; #define PG8_MMA(ai, bj, At, Bt) do { __builtin_amdgcn_s_setprio(1); _Pragma("unroll") for (int m = 0; m < 4; ++m) _Pragma("unroll") for (int n = 0; n < 2; ++n) _Pragma("unroll") for (int k = 0; k < 2; ++k) \
;         acc[ai][bj][m][n] = __builtin_amdgcn_mfma_f32_16x16x32_bf16(Bt[n][k], At[m][k], acc[ai][bj][m][n], 0, 0, 0); __builtin_amdgcn_s_setprio(0); } while (0)
; #define PG8_WAIT_V(n) asm volatile("s_waitcnt vmcnt(" #n ")" ::: "memory")
; #define PG8_WAIT_L(n) asm volatile("s_waitcnt lgkmcnt(" #n ")" ::: "memory")
; #define PG8_BAR __builtin_amdgcn_s_barrier()
; #define PG8_SCHED __builtin_amdgcn_sched_barrier(0)
; template <class Epi, class Sched>
; __device__ __forceinline__ void gemm_phase(LAS unsigned char* lds, const Gemm g, const Sched& S, const Epi& E) {
;     ...
;             PG8_WAIT_V(8); PG8_WAIT_L(0); PG8_BAR; PG8_MMA(1, 0, At, B0); PG8_MMA(1, 1, At, B1); PG8_BAR; PG8_SCHED;
;             PG8_LDB(B0, 1, 0); PG8_LDB(B1, 1, 1); PG8_SCHED; PG8_LDA(At, 1, 0); PG8_STAGE(PG8_SA(0, 1), a2 + hA, voffA);
;             PG8_WAIT_V(8); PG8_WAIT_L(0); PG8_BAR; PG8_MMA(0, 0, At, B0); PG8_MMA(0, 1, At, B1); PG8_BAR; PG8_SCHED;
	s_setprio 0
	s_waitcnt lgkmcnt(0)
	v_mfma_f32_16x16x32_bf16 v[60:63], v[128:131], v[190:193], v[60:63]
	v_mfma_f32_16x16x32_bf16 v[56:59], v[136:139], v[190:193], v[56:59]
	v_mfma_f32_16x16x32_bf16 v[52:55], v[128:131], v[198:201], v[52:55]
	v_mfma_f32_16x16x32_bf16 v[40:43], v[136:139], v[198:201], v[40:43]
	v_mfma_f32_16x16x32_bf16 v[36:39], v[128:131], v[206:209], v[36:39]
	v_mfma_f32_16x16x32_bf16 v[24:27], v[136:139], v[206:209], v[24:27]
	v_mfma_f32_16x16x32_bf16 v[20:23], v[128:131], v[214:217], v[20:23]
	v_mfma_f32_16x16x32_bf16 v[8:11], v[136:139], v[214:217], v[8:11]
	v_mfma_f32_16x16x32_bf16 v[60:63], v[132:135], v[194:197], v[60:63]
	v_mfma_f32_16x16x32_bf16 v[56:59], v[140:143], v[194:197], v[56:59]
	v_mfma_f32_16x16x32_bf16 v[52:55], v[132:135], v[202:205], v[52:55]
	v_mfma_f32_16x16x32_bf16 v[40:43], v[140:143], v[202:205], v[40:43]
	v_mfma_f32_16x16x32_bf16 v[36:39], v[132:135], v[210:213], v[36:39]
	v_mfma_f32_16x16x32_bf16 v[24:27], v[140:143], v[210:213], v[24:27]
	v_mfma_f32_16x16x32_bf16 v[20:23], v[132:135], v[220:223], v[20:23]
	v_mfma_f32_16x16x32_bf16 v[8:11], v[140:143], v[220:223], v[8:11]
	s_setprio 0
	s_setprio 0
	v_mfma_f32_16x16x32_bf16 v[48:51], v[174:177], v[190:193], v[48:51]
	v_mfma_f32_16x16x32_bf16 v[44:47], v[182:185], v[190:193], v[44:47]
	v_mfma_f32_16x16x32_bf16 v[32:35], v[174:177], v[198:201], v[32:35]
	v_mfma_f32_16x16x32_bf16 v[28:31], v[182:185], v[198:201], v[28:31]
	v_mfma_f32_16x16x32_bf16 v[16:19], v[174:177], v[206:209], v[16:19]
	v_mfma_f32_16x16x32_bf16 v[12:15], v[182:185], v[206:209], v[12:15]
	v_mfma_f32_16x16x32_bf16 v[4:7], v[174:177], v[214:217], v[4:7]
	v_mfma_f32_16x16x32_bf16 v[0:3], v[182:185], v[214:217], v[0:3]
	v_mfma_f32_16x16x32_bf16 v[48:51], v[178:181], v[194:197], v[48:51]
	v_mfma_f32_16x16x32_bf16 v[44:47], v[186:189], v[194:197], v[44:47]
	v_mfma_f32_16x16x32_bf16 v[32:35], v[178:181], v[202:205], v[32:35]
	v_mfma_f32_16x16x32_bf16 v[28:31], v[186:189], v[202:205], v[28:31]
	v_mfma_f32_16x16x32_bf16 v[16:19], v[178:181], v[210:213], v[16:19]
	v_mfma_f32_16x16x32_bf16 v[12:15], v[186:189], v[210:213], v[12:15]
	v_mfma_f32_16x16x32_bf16 v[4:7], v[178:181], v[220:223], v[4:7]
	v_mfma_f32_16x16x32_bf16 v[0:3], v[186:189], v[220:223], v[0:3]
	s_setprio 0
	s_barrier
	s_add_i32 s64, 0, 0x18000
	s_add_i32 s65, 0, 0x1c000
	v_add_u32_e32 v140, s64, v169
	v_add_u32_e32 v186, s65, v169
	ds_read_b128 v[128:131], v140
	ds_read_b128 v[132:135], v140 offset:1024
	ds_read_b128 v[136:139], v140 offset:2048
	ds_read_b128 v[140:143], v140 offset:3072
	ds_read_b128 v[174:177], v186
	ds_read_b128 v[178:181], v186 offset:1024
	ds_read_b128 v[182:185], v186 offset:2048
	ds_read_b128 v[186:189], v186 offset:3072
	s_add_u32 s18, s18, 0x80000
	s_addc_u32 s19, s19, 0
	s_mov_b32 m0, s50
	v_lshl_add_u64 v[230:231], s[18:19], 0, v[144:145]
	ds_read_b128 v[190:193], v173 offset:32768
	ds_read_b128 v[194:197], v173 offset:33792
	ds_read_b128 v[198:201], v173 offset:34816
	ds_read_b128 v[202:205], v173 offset:35840
	ds_read_b128 v[206:209], v173 offset:36864
	ds_read_b128 v[210:213], v173 offset:37888
	ds_read_b128 v[214:217], v173 offset:38912
	ds_read_b128 v[220:223], v173 offset:39936
	global_load_lds_dwordx4 v[230:231], off
	v_lshl_add_u64 v[230:231], s[18:19], 0, v[148:149]
	s_mov_b32 m0, s51
	s_nop 0
	global_load_lds_dwordx4 v[230:231], off
	s_waitcnt vmcnt(8)
	s_waitcnt lgkmcnt(0)
	s_barrier
	s_setprio 0
	s_waitcnt lgkmcnt(0)
	v_mfma_f32_16x16x32_bf16 v[124:127], v[128:131], v[190:193], v[124:127]
	v_mfma_f32_16x16x32_bf16 v[120:123], v[136:139], v[190:193], v[120:123]
	v_mfma_f32_16x16x32_bf16 v[116:119], v[128:131], v[198:201], v[116:119]
	v_mfma_f32_16x16x32_bf16 v[104:107], v[136:139], v[198:201], v[104:107]
	v_mfma_f32_16x16x32_bf16 v[100:103], v[128:131], v[206:209], v[100:103]
	v_mfma_f32_16x16x32_bf16 v[88:91], v[136:139], v[206:209], v[88:91]
	v_mfma_f32_16x16x32_bf16 v[84:87], v[128:131], v[214:217], v[84:87]
	v_mfma_f32_16x16x32_bf16 v[72:75], v[136:139], v[214:217], v[72:75]
	v_mfma_f32_16x16x32_bf16 v[124:127], v[132:135], v[194:197], v[124:127]
	v_mfma_f32_16x16x32_bf16 v[120:123], v[140:143], v[194:197], v[120:123]
	v_mfma_f32_16x16x32_bf16 v[116:119], v[132:135], v[202:205], v[116:119]
	v_mfma_f32_16x16x32_bf16 v[104:107], v[140:143], v[202:205], v[104:107]
	v_mfma_f32_16x16x32_bf16 v[100:103], v[132:135], v[210:213], v[100:103]
	v_mfma_f32_16x16x32_bf16 v[88:91], v[140:143], v[210:213], v[88:91]
	v_mfma_f32_16x16x32_bf16 v[84:87], v[132:135], v[220:223], v[84:87]
	v_mfma_f32_16x16x32_bf16 v[72:75], v[140:143], v[220:223], v[72:75]
	s_setprio 0
	s_setprio 0
	v_mfma_f32_16x16x32_bf16 v[112:115], v[174:177], v[190:193], v[112:115]
	v_mfma_f32_16x16x32_bf16 v[108:111], v[182:185], v[190:193], v[108:111]
	v_mfma_f32_16x16x32_bf16 v[96:99], v[174:177], v[198:201], v[96:99]
	v_mfma_f32_16x16x32_bf16 v[92:95], v[182:185], v[198:201], v[92:95]
	v_mfma_f32_16x16x32_bf16 v[80:83], v[174:177], v[206:209], v[80:83]
	v_mfma_f32_16x16x32_bf16 v[76:79], v[182:185], v[206:209], v[76:79]
	v_mfma_f32_16x16x32_bf16 v[68:71], v[174:177], v[214:217], v[68:71]
	v_mfma_f32_16x16x32_bf16 v[64:67], v[182:185], v[214:217], v[64:67]
	v_mfma_f32_16x16x32_bf16 v[112:115], v[178:181], v[194:197], v[112:115]
	v_mfma_f32_16x16x32_bf16 v[108:111], v[186:189], v[194:197], v[108:111]
	v_mfma_f32_16x16x32_bf16 v[96:99], v[178:181], v[202:205], v[96:99]
	v_mfma_f32_16x16x32_bf16 v[92:95], v[186:189], v[202:205], v[92:95]
	v_mfma_f32_16x16x32_bf16 v[80:83], v[178:181], v[210:213], v[80:83]
	v_mfma_f32_16x16x32_bf16 v[76:79], v[186:189], v[210:213], v[76:79]
	v_mfma_f32_16x16x32_bf16 v[68:71], v[178:181], v[220:223], v[68:71]
	v_mfma_f32_16x16x32_bf16 v[64:67], v[186:189], v[220:223], v[64:67]
	s_setprio 0
	s_barrier
; #define PG8_STAGE(bufoff, gbase, voff) do { _Pragma("unroll") for (int _i = 0; _i < 2; ++_i) \
;         __builtin_amdgcn_global_load_lds((const unsigned*)((const char*)(gbase) + (voff)[_i]), (LAS unsigned*)(lds + (bufoff) + ldsw + _i * 8192), 16, 0, 0); } while (0)
; #define PG8_LDA(dst, b, h) do { _Pragma("unroll") for (int m = 0; m < 4; ++m) _Pragma("unroll") for (int k = 0; k < 2; ++k) dst[m][k] = *(const LAS bf16x8*)(lds + PG8_SA(b, h) + aoff + m * 2048 + k * 1024); } while (0)
; #define PG8_MMA(ai, bj, At, Bt) do { __builtin_amdgcn_s_setprio(1); _Pragma("unroll") for (int m = 0; m < 4; ++m) _Pragma("unroll") for (int n = 0; n < 2; ++n) _Pragma("unroll") for (int k = 0; k < 2; ++k) \
;         acc[ai][bj][m][n] = __builtin_amdgcn_mfma_f32_16x16x32_bf16(Bt[n][k], At[m][k], acc[ai][bj][m][n], 0, 0, 0); __builtin_amdgcn_s_setprio(0); } while (0)
; #define PG8_WAIT_V(n) asm volatile("s_waitcnt vmcnt(" #n ")" ::: "memory")
; #define PG8_WAIT_L(n) asm volatile("s_waitcnt lgkmcnt(" #n ")" ::: "memory")
; #define PG8_BAR __builtin_amdgcn_s_barrier()
; #define PG8_SCHED __builtin_amdgcn_sched_barrier(0)
; template <class Epi, class Sched>
; __device__ __forceinline__ void gemm_phase(LAS unsigned char* lds, const Gemm g, const Sched& S, const Epi& E) {
;     ...
;             PG8_LDA(At, 1, 1); PG8_STAGE(PG8_SB(1, 0), b3, voffB); PG8_STAGE(PG8_SB(1, 1), b3 + hB, voffB); PG8_STAGE(PG8_SA(1, 0), a3, voffA);
;             PG8_WAIT_V(8); PG8_WAIT_L(0); PG8_BAR; PG8_MMA(1, 0, At, B0); PG8_MMA(1, 1, At, B1); PG8_BAR; PG8_SCHED;
;         }
;         if (wr == 0) PG8_BAR;
	s_add_i32 s18, s64, s33
	v_lshl_add_u64 v[160:161], v[160:161], 0, s[8:9]
	s_mov_b32 m0, s18
	ds_read_b128 v[190:193], v173 offset:49152
	ds_read_b128 v[194:197], v173 offset:50176
	ds_read_b128 v[198:201], v173 offset:51200
	ds_read_b128 v[202:205], v173 offset:52224
	ds_read_b128 v[206:209], v173 offset:53248
	ds_read_b128 v[210:213], v173 offset:54272
	ds_read_b128 v[214:217], v173 offset:55296
	ds_read_b128 v[220:223], v173 offset:56320
	global_load_lds_dwordx4 v[160:161], off
	s_add_i32 m0, s18, 0x2000
	s_add_u32 s0, s0, 0x80080
	v_lshl_add_u64 v[160:161], v[224:225], 0, s[8:9]
	s_addc_u32 s1, s1, 0
	s_add_i32 s18, s65, s33
	global_load_lds_dwordx4 v[160:161], off
	v_lshl_add_u64 v[160:161], s[0:1], 0, v[146:147]
	s_mov_b32 m0, s18
	s_nop 0
	global_load_lds_dwordx4 v[160:161], off
	v_lshl_add_u64 v[160:161], s[0:1], 0, v[150:151]
	s_add_i32 m0, s18, 0x2000
	s_nop 0
	global_load_lds_dwordx4 v[160:161], off
	v_lshl_add_u64 v[160:161], v[226:227], 0, s[8:9]
	s_mov_b32 m0, s56
	s_nop 0
	global_load_lds_dwordx4 v[160:161], off
	v_lshl_add_u64 v[160:161], v[228:229], 0, s[8:9]
	s_mov_b32 m0, s57
	s_nop 0
	global_load_lds_dwordx4 v[160:161], off
	s_waitcnt vmcnt(8)
	s_waitcnt lgkmcnt(0)
	s_barrier
	s_setprio 0
	s_waitcnt lgkmcnt(0)
	v_mfma_f32_16x16x32_bf16 v[60:63], v[128:131], v[190:193], v[60:63]
	v_mfma_f32_16x16x32_bf16 v[56:59], v[136:139], v[190:193], v[56:59]
	v_mfma_f32_16x16x32_bf16 v[52:55], v[128:131], v[198:201], v[52:55]
	v_mfma_f32_16x16x32_bf16 v[40:43], v[136:139], v[198:201], v[40:43]
	v_mfma_f32_16x16x32_bf16 v[36:39], v[128:131], v[206:209], v[36:39]
	v_mfma_f32_16x16x32_bf16 v[24:27], v[136:139], v[206:209], v[24:27]
	v_mfma_f32_16x16x32_bf16 v[20:23], v[128:131], v[214:217], v[20:23]
	v_mfma_f32_16x16x32_bf16 v[8:11], v[136:139], v[214:217], v[8:11]
	v_mfma_f32_16x16x32_bf16 v[60:63], v[132:135], v[194:197], v[60:63]
	v_mfma_f32_16x16x32_bf16 v[56:59], v[140:143], v[194:197], v[56:59]
	v_mfma_f32_16x16x32_bf16 v[52:55], v[132:135], v[202:205], v[52:55]
	v_mfma_f32_16x16x32_bf16 v[40:43], v[140:143], v[202:205], v[40:43]
	v_mfma_f32_16x16x32_bf16 v[36:39], v[132:135], v[210:213], v[36:39]
	v_mfma_f32_16x16x32_bf16 v[24:27], v[140:143], v[210:213], v[24:27]
	v_mfma_f32_16x16x32_bf16 v[20:23], v[132:135], v[220:223], v[20:23]
	v_mfma_f32_16x16x32_bf16 v[8:11], v[140:143], v[220:223], v[8:11]
	s_setprio 0
	s_setprio 0
	v_mfma_f32_16x16x32_bf16 v[48:51], v[174:177], v[190:193], v[48:51]
	v_mfma_f32_16x16x32_bf16 v[44:47], v[182:185], v[190:193], v[44:47]
	v_mfma_f32_16x16x32_bf16 v[32:35], v[174:177], v[198:201], v[32:35]
	v_mfma_f32_16x16x32_bf16 v[28:31], v[182:185], v[198:201], v[28:31]
	v_mfma_f32_16x16x32_bf16 v[16:19], v[174:177], v[206:209], v[16:19]
	v_mfma_f32_16x16x32_bf16 v[12:15], v[182:185], v[206:209], v[12:15]
	v_mfma_f32_16x16x32_bf16 v[4:7], v[174:177], v[214:217], v[4:7]
	v_mfma_f32_16x16x32_bf16 v[0:3], v[182:185], v[214:217], v[0:3]
	v_mfma_f32_16x16x32_bf16 v[48:51], v[178:181], v[194:197], v[48:51]
	v_mfma_f32_16x16x32_bf16 v[44:47], v[186:189], v[194:197], v[44:47]
	v_mfma_f32_16x16x32_bf16 v[32:35], v[178:181], v[202:205], v[32:35]
	v_mfma_f32_16x16x32_bf16 v[28:31], v[186:189], v[202:205], v[28:31]
	v_mfma_f32_16x16x32_bf16 v[16:19], v[178:181], v[210:213], v[16:19]
	v_mfma_f32_16x16x32_bf16 v[12:15], v[186:189], v[210:213], v[12:15]
	v_mfma_f32_16x16x32_bf16 v[4:7], v[178:181], v[220:223], v[4:7]
	v_mfma_f32_16x16x32_bf16 v[0:3], v[186:189], v[220:223], v[0:3]
	s_setprio 0
	s_barrier
	s_add_i32 s63, s63, 2
	s_add_u32 s46, s46, 0x100
	s_addc_u32 s47, s47, 0
	s_add_u32 s48, s48, 0x100
	s_addc_u32 s49, s49, 0
	s_cmp_gt_u32 s63, 29
	s_cbranch_scc0 .LBB0_822
	s_and_b64 vcc, exec, s[16:17]
	s_cbranch_vccz .LBB0_825
	s_barrier

; #define PG8_STAGE(bufoff, gbase, voff) do { _Pragma("unroll") for (int _i = 0; _i < 2; ++_i) \
;         __builtin_amdgcn_global_load_lds((const unsigned*)((const char*)(gbase) + (voff)[_i]), (LAS unsigned*)(lds + (bufoff) + ldsw + _i * 8192), 16, 0, 0); } while (0)
; #define PG8_LDA(dst, b, h) do { _Pragma("unroll") for (int m = 0; m < 4; ++m) _Pragma("unroll") for (int k = 0; k < 2; ++k) dst[m][k] = *(const LAS bf16x8*)(lds + PG8_SA(b, h) + aoff + m * 2048 + k * 1024); } while (0)
; #define PG8_LDB(dst, b, h) do { _Pragma("unroll") for (int n = 0; n < 2; ++n) _Pragma("unroll") for (int k = 0; k < 2; ++k) dst[n][k] = *(const LAS bf16x8*)(lds + PG8_SB(b, h) + boff + n * 2048 + k * 1024); } while (0)
; #define PG8_MMA(ai, bj, At, Bt) do { __builtin_amdgcn_s_setprio(1); _Pragma("unroll") for (int m = 0; m < 4; ++m) _Pragma("unroll") for (int n = 0; n < 2; ++n) _Pragma("unroll") for (int k = 0; k < 2; ++k) \
;         acc[ai][bj][m][n] = __builtin_amdgcn_mfma_f32_16x16x32_bf16(Bt[n][k], At[m][k], acc[ai][bj][m][n], 0, 0, 0); __builtin_amdgcn_s_setprio(0); } while (0)
; #define PG8_WAIT_V(n) asm volatile("s_waitcnt vmcnt(" #n ")" ::: "memory")
; #define PG8_WAIT_L(n) asm volatile("s_waitcnt lgkmcnt(" #n ")" ::: "memory")
; #define PG8_BAR __builtin_amdgcn_s_barrier()
; #define PG8_SCHED __builtin_amdgcn_sched_barrier(0)
; template <class Epi, class Sched>
; __device__ __forceinline__ void gemm_phase(LAS unsigned char* lds, const Gemm g, const Sched& S, const Epi& E) {
;     ...
;             PG8_LDB(B0, 0, 0); PG8_LDB(B1, 0, 1); PG8_SCHED; PG8_LDA(At, 0, 0); PG8_STAGE(PG8_SA(1, 1), a1 + hA, voffA);
;             PG8_WAIT_V(8); PG8_WAIT_L(0); PG8_BAR; PG8_MMA(0, 0, At, B0); PG8_MMA(0, 1, At, B1); PG8_BAR; PG8_SCHED;
;             PG8_LDA(At, 0, 1); PG8_STAGE(PG8_SB(0, 0), b2, voffB); PG8_STAGE(PG8_SB(0, 1), b2 + hB, voffB); PG8_STAGE(PG8_SA(0, 0), a2, voffA);
;             PG8_WAIT_V(8); PG8_WAIT_L(0); PG8_BAR; PG8_MMA(1, 0, At, B0); PG8_MMA(1, 1, At, B1); PG8_BAR; PG8_SCHED;
.LBB0_969:
	ds_read_b128 v[150:153], v147
	ds_read_b128 v[154:157], v147 offset:1024
	ds_read_b128 v[158:161], v147 offset:2048
	ds_read_b128 v[162:165], v147 offset:3072
	ds_read_b128 v[166:169], v148
	ds_read_b128 v[170:173], v148 offset:1024
	ds_read_b128 v[174:177], v148 offset:2048
	ds_read_b128 v[178:181], v148 offset:3072
	s_add_u32 s0, s26, 0xfff80080
	s_addc_u32 s1, s27, -1
	s_cmp_eq_u32 s49, 28
	s_cselect_b32 s29, s19, s1
	s_cselect_b32 s28, s45, s0
	s_cselect_b32 s1, s17, s48
	s_cselect_b32 s0, s46, s47
	v_lshl_add_u64 v[214:215], s[26:27], 0, v[136:137]
	s_add_i32 m0, s25, 0xc000
	ds_read_b128 v[182:185], v149
	ds_read_b128 v[186:189], v149 offset:1024
	ds_read_b128 v[190:193], v149 offset:2048
	ds_read_b128 v[194:197], v149 offset:3072
	ds_read_b128 v[198:201], v149 offset:4096
	ds_read_b128 v[202:205], v149 offset:5120
	ds_read_b128 v[206:209], v149 offset:6144
	ds_read_b128 v[210:213], v149 offset:7168
	global_load_lds_dwordx4 v[214:215], off
	v_lshl_add_u64 v[214:215], s[26:27], 0, v[138:139]
	s_add_i32 m0, s25, 0xe000
	s_nop 0
	global_load_lds_dwordx4 v[214:215], off
	s_waitcnt vmcnt(8)
	s_waitcnt lgkmcnt(0)
	s_barrier
	s_setprio 0
	s_waitcnt lgkmcnt(0)
	v_mfma_f32_16x16x32_bf16 v[124:127], v[150:153], v[182:185], v[124:127]
	v_mfma_f32_16x16x32_bf16 v[120:123], v[158:161], v[182:185], v[120:123]
	v_mfma_f32_16x16x32_bf16 v[108:111], v[150:153], v[190:193], v[108:111]
	v_mfma_f32_16x16x32_bf16 v[104:107], v[158:161], v[190:193], v[104:107]
	v_mfma_f32_16x16x32_bf16 v[92:95], v[150:153], v[198:201], v[92:95]
	v_mfma_f32_16x16x32_bf16 v[88:91], v[158:161], v[198:201], v[88:91]
	v_mfma_f32_16x16x32_bf16 v[76:79], v[150:153], v[206:209], v[76:79]
	v_mfma_f32_16x16x32_bf16 v[72:75], v[158:161], v[206:209], v[72:75]
	v_mfma_f32_16x16x32_bf16 v[124:127], v[154:157], v[186:189], v[124:127]
	v_mfma_f32_16x16x32_bf16 v[120:123], v[162:165], v[186:189], v[120:123]
	v_mfma_f32_16x16x32_bf16 v[108:111], v[154:157], v[194:197], v[108:111]
	v_mfma_f32_16x16x32_bf16 v[104:107], v[162:165], v[194:197], v[104:107]
	v_mfma_f32_16x16x32_bf16 v[92:95], v[154:157], v[202:205], v[92:95]
	v_mfma_f32_16x16x32_bf16 v[88:91], v[162:165], v[202:205], v[88:91]
	v_mfma_f32_16x16x32_bf16 v[76:79], v[154:157], v[210:213], v[76:79]
	v_mfma_f32_16x16x32_bf16 v[72:75], v[162:165], v[210:213], v[72:75]
	s_setprio 0
	s_setprio 0
	v_mfma_f32_16x16x32_bf16 v[116:119], v[166:169], v[182:185], v[116:119]
	v_mfma_f32_16x16x32_bf16 v[112:115], v[174:177], v[182:185], v[112:115]
	v_mfma_f32_16x16x32_bf16 v[100:103], v[166:169], v[190:193], v[100:103]
	v_mfma_f32_16x16x32_bf16 v[96:99], v[174:177], v[190:193], v[96:99]
	v_mfma_f32_16x16x32_bf16 v[84:87], v[166:169], v[198:201], v[84:87]
	v_mfma_f32_16x16x32_bf16 v[80:83], v[174:177], v[198:201], v[80:83]
	v_mfma_f32_16x16x32_bf16 v[68:71], v[166:169], v[206:209], v[68:71]
	v_mfma_f32_16x16x32_bf16 v[64:67], v[174:177], v[206:209], v[64:67]
	v_mfma_f32_16x16x32_bf16 v[116:119], v[170:173], v[186:189], v[116:119]
	v_mfma_f32_16x16x32_bf16 v[112:115], v[178:181], v[186:189], v[112:115]
	v_mfma_f32_16x16x32_bf16 v[100:103], v[170:173], v[194:197], v[100:103]
	v_mfma_f32_16x16x32_bf16 v[96:99], v[178:181], v[194:197], v[96:99]
	v_mfma_f32_16x16x32_bf16 v[84:87], v[170:173], v[202:205], v[84:87]
	v_mfma_f32_16x16x32_bf16 v[80:83], v[178:181], v[202:205], v[80:83]
	v_mfma_f32_16x16x32_bf16 v[68:71], v[170:173], v[210:213], v[68:71]
	v_mfma_f32_16x16x32_bf16 v[64:67], v[178:181], v[210:213], v[64:67]
	s_setprio 0
	s_barrier
	s_add_i32 s50, s41, s30
	v_lshl_add_u64 v[214:215], s[0:1], 0, v[130:131]
	s_mov_b32 m0, s50
	ds_read_b128 v[182:185], v149 offset:16384
	ds_read_b128 v[186:189], v149 offset:17408
	ds_read_b128 v[190:193], v149 offset:18432
	ds_read_b128 v[194:197], v149 offset:19456
	ds_read_b128 v[198:201], v149 offset:20480
	ds_read_b128 v[202:205], v149 offset:21504
	ds_read_b128 v[206:209], v149 offset:22528
	ds_read_b128 v[210:213], v149 offset:23552
	global_load_lds_dwordx4 v[214:215], off
	s_add_i32 m0, s50, 0x2000
	s_add_u32 s50, s0, 0x80000
	v_lshl_add_u64 v[216:217], s[0:1], 0, v[134:135]
	s_addc_u32 s51, s1, 0
	s_add_i32 s52, s42, s30
	global_load_lds_dwordx4 v[216:217], off
	v_lshl_add_u64 v[220:221], s[50:51], 0, v[130:131]
	s_mov_b32 m0, s52
	v_lshl_add_u64 v[222:223], s[28:29], 0, v[132:133]
	global_load_lds_dwordx4 v[220:221], off
	v_lshl_add_u64 v[220:221], s[50:51], 0, v[134:135]
	s_add_i32 m0, s52, 0x2000
	s_nop 0
	global_load_lds_dwordx4 v[220:221], off
	v_lshl_add_u64 v[220:221], s[28:29], 0, v[128:129]
	s_mov_b32 m0, s25
	s_nop 0
	global_load_lds_dwordx4 v[220:221], off
	s_mov_b32 m0, s34
	s_nop 0
	global_load_lds_dwordx4 v[222:223], off
	s_waitcnt vmcnt(8)
	s_waitcnt lgkmcnt(0)
	s_barrier
; #define PG8_STAGE(bufoff, gbase, voff) do { _Pragma("unroll") for (int _i = 0; _i < 2; ++_i) \
;         __builtin_amdgcn_global_load_lds((const unsigned*)((const char*)(gbase) + (voff)[_i]), (LAS unsigned*)(lds + (bufoff) + ldsw + _i * 8192), 16, 0, 0); } while (0)
; #define PG8_LDA(dst, b, h) do { _Pragma("unroll") for (int m = 0; m < 4; ++m) _Pragma("unroll") for (int k = 0; k < 2; ++k) dst[m][k] = *(const LAS bf16x8*)(lds + PG8_SA(b, h) + aoff + m * 2048 + k * 1024); } while (0)
; #define PG8_LDB(dst, b, h) do { _Pragma("unroll") for (int n = 0; n < 2; ++n) _Pragma("unroll") for (int k = 0; k < 2; ++k) dst[n][k] = *(const LAS bf16x8*)(lds + PG8_SB(b, h) + boff + n * 2048 + k * 1024); } while (0)
; #define PG8_MMA(ai, bj, At, Bt) do { __builtin_amdgcn_s_setprio(1); _Pragma("unroll") for (int m = 0; m < 4; ++m) _Pragma("unroll") for (int n = 0; n < 2; ++n) _Pragma("unroll") for (int k = 0; k < 2; ++k) \
;         acc[ai][bj][m][n] = __builtin_amdgcn_mfma_f32_16x16x32_bf16(Bt[n][k], At[m][k], acc[ai][bj][m][n], 0, 0, 0); __builtin_amdgcn_s_setprio(0); } while (0)
; #define PG8_WAIT_V(n) asm volatile("s_waitcnt vmcnt(" #n ")" ::: "memory")
; #define PG8_WAIT_L(n) asm volatile("s_waitcnt lgkmcnt(" #n ")" ::: "memory")
; #define PG8_BAR __builtin_amdgcn_s_barrier()
; #define PG8_SCHED __builtin_amdgcn_sched_barrier(0)
; template <class Epi, class Sched>
; __device__ __forceinline__ void gemm_phase(LAS unsigned char* lds, const Gemm g, const Sched& S, const Epi& E) {
;     ...
;             PG8_WAIT_V(8); PG8_WAIT_L(0); PG8_BAR; PG8_MMA(1, 0, At, B0); PG8_MMA(1, 1, At, B1); PG8_BAR; PG8_SCHED;
;             PG8_LDB(B0, 1, 0); PG8_LDB(B1, 1, 1); PG8_SCHED; PG8_LDA(At, 1, 0); PG8_STAGE(PG8_SA(0, 1), a2 + hA, voffA);
;             PG8_WAIT_V(8); PG8_WAIT_L(0); PG8_BAR; PG8_MMA(0, 0, At, B0); PG8_MMA(0, 1, At, B1); PG8_BAR; PG8_SCHED;
	s_setprio 0
	s_waitcnt lgkmcnt(0)
	v_mfma_f32_16x16x32_bf16 v[60:63], v[150:153], v[182:185], v[60:63]
	v_mfma_f32_16x16x32_bf16 v[56:59], v[158:161], v[182:185], v[56:59]
	v_mfma_f32_16x16x32_bf16 v[44:47], v[150:153], v[190:193], v[44:47]
	v_mfma_f32_16x16x32_bf16 v[40:43], v[158:161], v[190:193], v[40:43]
	v_mfma_f32_16x16x32_bf16 v[28:31], v[150:153], v[198:201], v[28:31]
	v_mfma_f32_16x16x32_bf16 v[24:27], v[158:161], v[198:201], v[24:27]
	v_mfma_f32_16x16x32_bf16 v[12:15], v[150:153], v[206:209], v[12:15]
	v_mfma_f32_16x16x32_bf16 v[8:11], v[158:161], v[206:209], v[8:11]
	v_mfma_f32_16x16x32_bf16 v[60:63], v[154:157], v[186:189], v[60:63]
	v_mfma_f32_16x16x32_bf16 v[56:59], v[162:165], v[186:189], v[56:59]
	v_mfma_f32_16x16x32_bf16 v[44:47], v[154:157], v[194:197], v[44:47]
	v_mfma_f32_16x16x32_bf16 v[40:43], v[162:165], v[194:197], v[40:43]
	v_mfma_f32_16x16x32_bf16 v[28:31], v[154:157], v[202:205], v[28:31]
	v_mfma_f32_16x16x32_bf16 v[24:27], v[162:165], v[202:205], v[24:27]
	v_mfma_f32_16x16x32_bf16 v[12:15], v[154:157], v[210:213], v[12:15]
	v_mfma_f32_16x16x32_bf16 v[8:11], v[162:165], v[210:213], v[8:11]
	s_setprio 0
	s_setprio 0
	v_mfma_f32_16x16x32_bf16 v[52:55], v[166:169], v[182:185], v[52:55]
	v_mfma_f32_16x16x32_bf16 v[48:51], v[174:177], v[182:185], v[48:51]
	v_mfma_f32_16x16x32_bf16 v[36:39], v[166:169], v[190:193], v[36:39]
	v_mfma_f32_16x16x32_bf16 v[32:35], v[174:177], v[190:193], v[32:35]
	v_mfma_f32_16x16x32_bf16 v[20:23], v[166:169], v[198:201], v[20:23]
	v_mfma_f32_16x16x32_bf16 v[16:19], v[174:177], v[198:201], v[16:19]
	v_mfma_f32_16x16x32_bf16 v[4:7], v[166:169], v[206:209], v[4:7]
	v_mfma_f32_16x16x32_bf16 v[0:3], v[174:177], v[206:209], v[0:3]
	v_mfma_f32_16x16x32_bf16 v[52:55], v[170:173], v[186:189], v[52:55]
	v_mfma_f32_16x16x32_bf16 v[48:51], v[178:181], v[186:189], v[48:51]
	v_mfma_f32_16x16x32_bf16 v[36:39], v[170:173], v[194:197], v[36:39]
	v_mfma_f32_16x16x32_bf16 v[32:35], v[178:181], v[194:197], v[32:35]
	v_mfma_f32_16x16x32_bf16 v[20:23], v[170:173], v[202:205], v[20:23]
	v_mfma_f32_16x16x32_bf16 v[16:19], v[178:181], v[202:205], v[16:19]
	v_mfma_f32_16x16x32_bf16 v[4:7], v[170:173], v[210:213], v[4:7]
	v_mfma_f32_16x16x32_bf16 v[0:3], v[178:181], v[210:213], v[0:3]
	s_setprio 0
	s_barrier
	s_add_i32 s50, 0, 0x18000
	s_add_i32 s51, 0, 0x1c000
	v_add_u32_e32 v162, s50, v145
	v_add_u32_e32 v178, s51, v145
	ds_read_b128 v[150:153], v162
	ds_read_b128 v[154:157], v162 offset:1024
	ds_read_b128 v[158:161], v162 offset:2048
	ds_read_b128 v[162:165], v162 offset:3072
	ds_read_b128 v[166:169], v178
	ds_read_b128 v[170:173], v178 offset:1024
	ds_read_b128 v[174:177], v178 offset:2048
	ds_read_b128 v[178:181], v178 offset:3072
	s_add_u32 s28, s28, 0x80000
	s_addc_u32 s29, s29, 0
	s_mov_b32 m0, s35
	v_lshl_add_u64 v[224:225], s[28:29], 0, v[128:129]
	ds_read_b128 v[182:185], v149 offset:32768
	ds_read_b128 v[186:189], v149 offset:33792
	ds_read_b128 v[190:193], v149 offset:34816
	ds_read_b128 v[194:197], v149 offset:35840
	ds_read_b128 v[198:201], v149 offset:36864
	ds_read_b128 v[202:205], v149 offset:37888
	ds_read_b128 v[206:209], v149 offset:38912
	ds_read_b128 v[210:213], v149 offset:39936
	global_load_lds_dwordx4 v[224:225], off
	v_lshl_add_u64 v[224:225], s[28:29], 0, v[132:133]
	s_mov_b32 m0, s36
	s_nop 0
	global_load_lds_dwordx4 v[224:225], off
	s_waitcnt vmcnt(8)
	s_waitcnt lgkmcnt(0)
	s_barrier
	s_setprio 0
	s_waitcnt lgkmcnt(0)
	v_mfma_f32_16x16x32_bf16 v[124:127], v[150:153], v[182:185], v[124:127]
	v_mfma_f32_16x16x32_bf16 v[120:123], v[158:161], v[182:185], v[120:123]
	v_mfma_f32_16x16x32_bf16 v[108:111], v[150:153], v[190:193], v[108:111]
	v_mfma_f32_16x16x32_bf16 v[104:107], v[158:161], v[190:193], v[104:107]
	v_mfma_f32_16x16x32_bf16 v[92:95], v[150:153], v[198:201], v[92:95]
	v_mfma_f32_16x16x32_bf16 v[88:91], v[158:161], v[198:201], v[88:91]
	v_mfma_f32_16x16x32_bf16 v[76:79], v[150:153], v[206:209], v[76:79]
	v_mfma_f32_16x16x32_bf16 v[72:75], v[158:161], v[206:209], v[72:75]
	v_mfma_f32_16x16x32_bf16 v[124:127], v[154:157], v[186:189], v[124:127]
	v_mfma_f32_16x16x32_bf16 v[120:123], v[162:165], v[186:189], v[120:123]
	v_mfma_f32_16x16x32_bf16 v[108:111], v[154:157], v[194:197], v[108:111]
	v_mfma_f32_16x16x32_bf16 v[104:107], v[162:165], v[194:197], v[104:107]
	v_mfma_f32_16x16x32_bf16 v[92:95], v[154:157], v[202:205], v[92:95]
	v_mfma_f32_16x16x32_bf16 v[88:91], v[162:165], v[202:205], v[88:91]
	v_mfma_f32_16x16x32_bf16 v[76:79], v[154:157], v[210:213], v[76:79]
	v_mfma_f32_16x16x32_bf16 v[72:75], v[162:165], v[210:213], v[72:75]
	s_setprio 0
	s_setprio 0
	v_mfma_f32_16x16x32_bf16 v[116:119], v[166:169], v[182:185], v[116:119]
	v_mfma_f32_16x16x32_bf16 v[112:115], v[174:177], v[182:185], v[112:115]
	v_mfma_f32_16x16x32_bf16 v[100:103], v[166:169], v[190:193], v[100:103]
	v_mfma_f32_16x16x32_bf16 v[96:99], v[174:177], v[190:193], v[96:99]
	v_mfma_f32_16x16x32_bf16 v[84:87], v[166:169], v[198:201], v[84:87]
	v_mfma_f32_16x16x32_bf16 v[80:83], v[174:177], v[198:201], v[80:83]
	v_mfma_f32_16x16x32_bf16 v[68:71], v[166:169], v[206:209], v[68:71]
	v_mfma_f32_16x16x32_bf16 v[64:67], v[174:177], v[206:209], v[64:67]
	v_mfma_f32_16x16x32_bf16 v[116:119], v[170:173], v[186:189], v[116:119]
	v_mfma_f32_16x16x32_bf16 v[112:115], v[178:181], v[186:189], v[112:115]
	v_mfma_f32_16x16x32_bf16 v[100:103], v[170:173], v[194:197], v[100:103]
	v_mfma_f32_16x16x32_bf16 v[96:99], v[178:181], v[194:197], v[96:99]
	v_mfma_f32_16x16x32_bf16 v[84:87], v[170:173], v[202:205], v[84:87]
	v_mfma_f32_16x16x32_bf16 v[80:83], v[178:181], v[202:205], v[80:83]
	v_mfma_f32_16x16x32_bf16 v[68:71], v[170:173], v[210:213], v[68:71]
	v_mfma_f32_16x16x32_bf16 v[64:67], v[178:181], v[210:213], v[64:67]
	s_setprio 0
	s_barrier
; #define PG8_STAGE(bufoff, gbase, voff) do { _Pragma("unroll") for (int _i = 0; _i < 2; ++_i) \
;         __builtin_amdgcn_global_load_lds((const unsigned*)((const char*)(gbase) + (voff)[_i]), (LAS unsigned*)(lds + (bufoff) + ldsw + _i * 8192), 16, 0, 0); } while (0)
; #define PG8_LDA(dst, b, h) do { _Pragma("unroll") for (int m = 0; m < 4; ++m) _Pragma("unroll") for (int k = 0; k < 2; ++k) dst[m][k] = *(const LAS bf16x8*)(lds + PG8_SA(b, h) + aoff + m * 2048 + k * 1024); } while (0)
; #define PG8_MMA(ai, bj, At, Bt) do { __builtin_amdgcn_s_setprio(1); _Pragma("unroll") for (int m = 0; m < 4; ++m) _Pragma("unroll") for (int n = 0; n < 2; ++n) _Pragma("unroll") for (int k = 0; k < 2; ++k) \
;         acc[ai][bj][m][n] = __builtin_amdgcn_mfma_f32_16x16x32_bf16(Bt[n][k], At[m][k], acc[ai][bj][m][n], 0, 0, 0); __builtin_amdgcn_s_setprio(0); } while (0)
; #define PG8_WAIT_V(n) asm volatile("s_waitcnt vmcnt(" #n ")" ::: "memory")
; #define PG8_WAIT_L(n) asm volatile("s_waitcnt lgkmcnt(" #n ")" ::: "memory")
; #define PG8_BAR __builtin_amdgcn_s_barrier()
; #define PG8_SCHED __builtin_amdgcn_sched_barrier(0)
; template <class Epi, class Sched>
; __device__ __forceinline__ void gemm_phase(LAS unsigned char* lds, const Gemm g, const Sched& S, const Epi& E) {
;     ...
;             PG8_LDA(At, 1, 1); PG8_STAGE(PG8_SB(1, 0), b3, voffB); PG8_STAGE(PG8_SB(1, 1), b3 + hB, voffB); PG8_STAGE(PG8_SA(1, 0), a3, voffA);
;             PG8_WAIT_V(8); PG8_WAIT_L(0); PG8_BAR; PG8_MMA(1, 0, At, B0); PG8_MMA(1, 1, At, B1); PG8_BAR; PG8_SCHED;
;         }
;         if (wr == 0) PG8_BAR;
	s_add_i32 s28, s50, s30
	v_lshl_add_u64 v[214:215], v[214:215], 0, s[8:9]
	s_mov_b32 m0, s28
	ds_read_b128 v[182:185], v149 offset:49152
	ds_read_b128 v[186:189], v149 offset:50176
	ds_read_b128 v[190:193], v149 offset:51200
	ds_read_b128 v[194:197], v149 offset:52224
	ds_read_b128 v[198:201], v149 offset:53248
	ds_read_b128 v[202:205], v149 offset:54272
	ds_read_b128 v[206:209], v149 offset:55296
	ds_read_b128 v[210:213], v149 offset:56320
	global_load_lds_dwordx4 v[214:215], off
	s_add_i32 m0, s28, 0x2000
	s_add_u32 s0, s0, 0x80080
	v_lshl_add_u64 v[214:215], v[216:217], 0, s[8:9]
	s_addc_u32 s1, s1, 0
	s_add_i32 s28, s51, s30
	global_load_lds_dwordx4 v[214:215], off
	v_lshl_add_u64 v[214:215], s[0:1], 0, v[130:131]
	s_mov_b32 m0, s28
	s_nop 0
	global_load_lds_dwordx4 v[214:215], off
	v_lshl_add_u64 v[214:215], s[0:1], 0, v[134:135]
	s_add_i32 m0, s28, 0x2000
	s_nop 0
	global_load_lds_dwordx4 v[214:215], off
	v_lshl_add_u64 v[214:215], v[220:221], 0, s[8:9]
	s_mov_b32 m0, s39
	s_nop 0
	global_load_lds_dwordx4 v[214:215], off
	v_lshl_add_u64 v[214:215], v[222:223], 0, s[8:9]
	s_mov_b32 m0, s40
	s_nop 0
	global_load_lds_dwordx4 v[214:215], off
	s_waitcnt vmcnt(8)
	s_waitcnt lgkmcnt(0)
	s_barrier
	s_setprio 0
	s_waitcnt lgkmcnt(0)
	v_mfma_f32_16x16x32_bf16 v[60:63], v[150:153], v[182:185], v[60:63]
	v_mfma_f32_16x16x32_bf16 v[56:59], v[158:161], v[182:185], v[56:59]
	v_mfma_f32_16x16x32_bf16 v[44:47], v[150:153], v[190:193], v[44:47]
	v_mfma_f32_16x16x32_bf16 v[40:43], v[158:161], v[190:193], v[40:43]
	v_mfma_f32_16x16x32_bf16 v[28:31], v[150:153], v[198:201], v[28:31]
	v_mfma_f32_16x16x32_bf16 v[24:27], v[158:161], v[198:201], v[24:27]
	v_mfma_f32_16x16x32_bf16 v[12:15], v[150:153], v[206:209], v[12:15]
	v_mfma_f32_16x16x32_bf16 v[8:11], v[158:161], v[206:209], v[8:11]
	v_mfma_f32_16x16x32_bf16 v[60:63], v[154:157], v[186:189], v[60:63]
	v_mfma_f32_16x16x32_bf16 v[56:59], v[162:165], v[186:189], v[56:59]
	v_mfma_f32_16x16x32_bf16 v[44:47], v[154:157], v[194:197], v[44:47]
	v_mfma_f32_16x16x32_bf16 v[40:43], v[162:165], v[194:197], v[40:43]
	v_mfma_f32_16x16x32_bf16 v[28:31], v[154:157], v[202:205], v[28:31]
	v_mfma_f32_16x16x32_bf16 v[24:27], v[162:165], v[202:205], v[24:27]
	v_mfma_f32_16x16x32_bf16 v[12:15], v[154:157], v[210:213], v[12:15]
	v_mfma_f32_16x16x32_bf16 v[8:11], v[162:165], v[210:213], v[8:11]
	s_setprio 0
	s_setprio 0
	v_mfma_f32_16x16x32_bf16 v[52:55], v[166:169], v[182:185], v[52:55]
	v_mfma_f32_16x16x32_bf16 v[48:51], v[174:177], v[182:185], v[48:51]
	v_mfma_f32_16x16x32_bf16 v[36:39], v[166:169], v[190:193], v[36:39]
	v_mfma_f32_16x16x32_bf16 v[32:35], v[174:177], v[190:193], v[32:35]
	v_mfma_f32_16x16x32_bf16 v[20:23], v[166:169], v[198:201], v[20:23]
	v_mfma_f32_16x16x32_bf16 v[16:19], v[174:177], v[198:201], v[16:19]
	v_mfma_f32_16x16x32_bf16 v[4:7], v[166:169], v[206:209], v[4:7]
	v_mfma_f32_16x16x32_bf16 v[0:3], v[174:177], v[206:209], v[0:3]
	v_mfma_f32_16x16x32_bf16 v[52:55], v[170:173], v[186:189], v[52:55]
	v_mfma_f32_16x16x32_bf16 v[48:51], v[178:181], v[186:189], v[48:51]
	v_mfma_f32_16x16x32_bf16 v[36:39], v[170:173], v[194:197], v[36:39]
	v_mfma_f32_16x16x32_bf16 v[32:35], v[178:181], v[194:197], v[32:35]
	v_mfma_f32_16x16x32_bf16 v[20:23], v[170:173], v[202:205], v[20:23]
	v_mfma_f32_16x16x32_bf16 v[16:19], v[178:181], v[202:205], v[16:19]
	v_mfma_f32_16x16x32_bf16 v[4:7], v[170:173], v[210:213], v[4:7]
	v_mfma_f32_16x16x32_bf16 v[0:3], v[178:181], v[210:213], v[0:3]
	s_setprio 0
	s_barrier
	s_add_i32 s49, s49, 2
	s_add_u32 s26, s26, 0x100
	s_addc_u32 s27, s27, 0
	s_add_u32 s47, s47, 0x100
	s_addc_u32 s48, s48, 0
	s_cmp_gt_u32 s49, 29
	s_cbranch_scc0 .LBB0_969
	s_and_b64 vcc, exec, s[10:11]
	s_cbranch_vccz .LBB0_972
	s_barrier

; #define PG8_STAGE(bufoff, gbase, voff) do { _Pragma("unroll") for (int _i = 0; _i < 2; ++_i) \
;         __builtin_amdgcn_global_load_lds((const unsigned*)((const char*)(gbase) + (voff)[_i]), (LAS unsigned*)(lds + (bufoff) + ldsw + _i * 8192), 16, 0, 0); } while (0)
; #define PG8_LDA(dst, b, h) do { _Pragma("unroll") for (int m = 0; m < 4; ++m) _Pragma("unroll") for (int k = 0; k < 2; ++k) dst[m][k] = *(const LAS bf16x8*)(lds + PG8_SA(b, h) + aoff + m * 2048 + k * 1024); } while (0)
; #define PG8_LDB(dst, b, h) do { _Pragma("unroll") for (int n = 0; n < 2; ++n) _Pragma("unroll") for (int k = 0; k < 2; ++k) dst[n][k] = *(const LAS bf16x8*)(lds + PG8_SB(b, h) + boff + n * 2048 + k * 1024); } while (0)
; #define PG8_MMA(ai, bj, At, Bt) do { __builtin_amdgcn_s_setprio(1); _Pragma("unroll") for (int m = 0; m < 4; ++m) _Pragma("unroll") for (int n = 0; n < 2; ++n) _Pragma("unroll") for (int k = 0; k < 2; ++k) \
;         acc[ai][bj][m][n] = __builtin_amdgcn_mfma_f32_16x16x32_bf16(Bt[n][k], At[m][k], acc[ai][bj][m][n], 0, 0, 0); __builtin_amdgcn_s_setprio(0); } while (0)
; #define PG8_WAIT_V(n) asm volatile("s_waitcnt vmcnt(" #n ")" ::: "memory")
; #define PG8_WAIT_L(n) asm volatile("s_waitcnt lgkmcnt(" #n ")" ::: "memory")
; #define PG8_BAR __builtin_amdgcn_s_barrier()
; #define PG8_SCHED __builtin_amdgcn_sched_barrier(0)
; template <class Epi, class Sched>
; __device__ __forceinline__ void gemm_phase(LAS unsigned char* lds, const Gemm g, const Sched& S, const Epi& E) {
;     ...
;             PG8_LDB(B0, 0, 0); PG8_LDB(B1, 0, 1); PG8_SCHED; PG8_LDA(At, 0, 0); PG8_STAGE(PG8_SA(1, 1), a1 + hA, voffA);
;             PG8_WAIT_V(8); PG8_WAIT_L(0); PG8_BAR; PG8_MMA(0, 0, At, B0); PG8_MMA(0, 1, At, B1); PG8_BAR; PG8_SCHED;
;             PG8_LDA(At, 0, 1); PG8_STAGE(PG8_SB(0, 0), b2, voffB); PG8_STAGE(PG8_SB(0, 1), b2 + hB, voffB); PG8_STAGE(PG8_SA(0, 0), a2, voffA);
;             PG8_WAIT_V(8); PG8_WAIT_L(0); PG8_BAR; PG8_MMA(1, 0, At, B0); PG8_MMA(1, 1, At, B1); PG8_BAR; PG8_SCHED;
.LBB0_1048:
	ds_read_b128 v[128:131], v165
	ds_read_b128 v[132:135], v165 offset:1024
	ds_read_b128 v[136:139], v165 offset:2048
	ds_read_b128 v[140:143], v165 offset:3072
	ds_read_b128 v[168:171], v166
	ds_read_b128 v[172:175], v166 offset:1024
	ds_read_b128 v[176:179], v166 offset:2048
	ds_read_b128 v[180:183], v166 offset:3072
	s_add_u32 s26, s24, 0xffea0080
	s_addc_u32 s27, s25, -1
	s_cmpk_eq_i32 s55, 0x54
	s_cselect_b32 s29, s3, s27
	s_cselect_b32 s28, s2, s26
	s_cselect_b32 s27, s23, s54
	s_cselect_b32 s26, s22, s53
	v_lshl_add_u64 v[160:161], s[24:25], 0, v[152:153]
	s_add_i32 m0, s33, 0xc000
	ds_read_b128 v[184:187], v167
	ds_read_b128 v[188:191], v167 offset:1024
	ds_read_b128 v[192:195], v167 offset:2048
	ds_read_b128 v[196:199], v167 offset:3072
	ds_read_b128 v[200:203], v167 offset:4096
	ds_read_b128 v[204:207], v167 offset:5120
	ds_read_b128 v[208:211], v167 offset:6144
	ds_read_b128 v[212:215], v167 offset:7168
	global_load_lds_dwordx4 v[160:161], off
	v_lshl_add_u64 v[160:161], s[24:25], 0, v[154:155]
	s_add_i32 m0, s33, 0xe000
	s_nop 0
	global_load_lds_dwordx4 v[160:161], off
	s_waitcnt vmcnt(8)
	s_waitcnt lgkmcnt(0)
	s_barrier
	s_setprio 0
	s_waitcnt lgkmcnt(0)
	v_mfma_f32_16x16x32_bf16 v[124:127], v[128:131], v[184:187], v[124:127]
	v_mfma_f32_16x16x32_bf16 v[120:123], v[136:139], v[184:187], v[120:123]
	v_mfma_f32_16x16x32_bf16 v[108:111], v[128:131], v[192:195], v[108:111]
	v_mfma_f32_16x16x32_bf16 v[104:107], v[136:139], v[192:195], v[104:107]
	v_mfma_f32_16x16x32_bf16 v[92:95], v[128:131], v[200:203], v[92:95]
	v_mfma_f32_16x16x32_bf16 v[88:91], v[136:139], v[200:203], v[88:91]
	v_mfma_f32_16x16x32_bf16 v[76:79], v[128:131], v[208:211], v[76:79]
	v_mfma_f32_16x16x32_bf16 v[72:75], v[136:139], v[208:211], v[72:75]
	v_mfma_f32_16x16x32_bf16 v[124:127], v[132:135], v[188:191], v[124:127]
	v_mfma_f32_16x16x32_bf16 v[120:123], v[140:143], v[188:191], v[120:123]
	v_mfma_f32_16x16x32_bf16 v[108:111], v[132:135], v[196:199], v[108:111]
	v_mfma_f32_16x16x32_bf16 v[104:107], v[140:143], v[196:199], v[104:107]
	v_mfma_f32_16x16x32_bf16 v[92:95], v[132:135], v[204:207], v[92:95]
	v_mfma_f32_16x16x32_bf16 v[88:91], v[140:143], v[204:207], v[88:91]
	v_mfma_f32_16x16x32_bf16 v[76:79], v[132:135], v[212:215], v[76:79]
	v_mfma_f32_16x16x32_bf16 v[72:75], v[140:143], v[212:215], v[72:75]
	s_setprio 0
	s_setprio 0
	v_mfma_f32_16x16x32_bf16 v[116:119], v[168:171], v[184:187], v[116:119]
	v_mfma_f32_16x16x32_bf16 v[112:115], v[176:179], v[184:187], v[112:115]
	v_mfma_f32_16x16x32_bf16 v[100:103], v[168:171], v[192:195], v[100:103]
	v_mfma_f32_16x16x32_bf16 v[96:99], v[176:179], v[192:195], v[96:99]
	v_mfma_f32_16x16x32_bf16 v[84:87], v[168:171], v[200:203], v[84:87]
	v_mfma_f32_16x16x32_bf16 v[80:83], v[176:179], v[200:203], v[80:83]
	v_mfma_f32_16x16x32_bf16 v[68:71], v[168:171], v[208:211], v[68:71]
	v_mfma_f32_16x16x32_bf16 v[64:67], v[176:179], v[208:211], v[64:67]
	v_mfma_f32_16x16x32_bf16 v[116:119], v[172:175], v[188:191], v[116:119]
	v_mfma_f32_16x16x32_bf16 v[112:115], v[180:183], v[188:191], v[112:115]
	v_mfma_f32_16x16x32_bf16 v[100:103], v[172:175], v[196:199], v[100:103]
	v_mfma_f32_16x16x32_bf16 v[96:99], v[180:183], v[196:199], v[96:99]
	v_mfma_f32_16x16x32_bf16 v[84:87], v[172:175], v[204:207], v[84:87]
	v_mfma_f32_16x16x32_bf16 v[80:83], v[180:183], v[204:207], v[80:83]
	v_mfma_f32_16x16x32_bf16 v[68:71], v[172:175], v[212:215], v[68:71]
	v_mfma_f32_16x16x32_bf16 v[64:67], v[180:183], v[212:215], v[64:67]
	s_setprio 0
	s_barrier
	s_add_i32 s56, s43, s30
	v_lshl_add_u64 v[160:161], s[26:27], 0, v[146:147]
	s_mov_b32 m0, s56
	ds_read_b128 v[184:187], v167 offset:16384
	ds_read_b128 v[188:191], v167 offset:17408
	ds_read_b128 v[192:195], v167 offset:18432
	ds_read_b128 v[196:199], v167 offset:19456
	ds_read_b128 v[200:203], v167 offset:20480
	ds_read_b128 v[204:207], v167 offset:21504
	ds_read_b128 v[208:211], v167 offset:22528
	ds_read_b128 v[212:215], v167 offset:23552
	global_load_lds_dwordx4 v[160:161], off
	s_add_i32 m0, s56, 0x2000
	s_add_u32 s56, s26, 0x160000
	v_lshl_add_u64 v[216:217], s[26:27], 0, v[150:151]
	s_addc_u32 s57, s27, 0
	s_add_i32 s58, s44, s30
	global_load_lds_dwordx4 v[216:217], off
	v_lshl_add_u64 v[218:219], s[56:57], 0, v[146:147]
	s_mov_b32 m0, s58
	v_lshl_add_u64 v[220:221], s[28:29], 0, v[148:149]
	global_load_lds_dwordx4 v[218:219], off
	v_lshl_add_u64 v[218:219], s[56:57], 0, v[150:151]
	s_add_i32 m0, s58, 0x2000
	s_nop 0
	global_load_lds_dwordx4 v[218:219], off
	v_lshl_add_u64 v[218:219], s[28:29], 0, v[144:145]
	s_mov_b32 m0, s33
	s_nop 0
	global_load_lds_dwordx4 v[218:219], off
	s_mov_b32 m0, s34
	s_nop 0
	global_load_lds_dwordx4 v[220:221], off
	s_waitcnt vmcnt(8)
	s_waitcnt lgkmcnt(0)
	s_barrier
; #define PG8_STAGE(bufoff, gbase, voff) do { _Pragma("unroll") for (int _i = 0; _i < 2; ++_i) \
;         __builtin_amdgcn_global_load_lds((const unsigned*)((const char*)(gbase) + (voff)[_i]), (LAS unsigned*)(lds + (bufoff) + ldsw + _i * 8192), 16, 0, 0); } while (0)
; #define PG8_LDA(dst, b, h) do { _Pragma("unroll") for (int m = 0; m < 4; ++m) _Pragma("unroll") for (int k = 0; k < 2; ++k) dst[m][k] = *(const LAS bf16x8*)(lds + PG8_SA(b, h) + aoff + m * 2048 + k * 1024); } while (0)
; #define PG8_LDB(dst, b, h) do { _Pragma("unroll") for (int n = 0; n < 2; ++n) _Pragma("unroll") for (int k = 0; k < 2; ++k) dst[n][k] = *(const LAS bf16x8*)(lds + PG8_SB(b, h) + boff + n * 2048 + k * 1024); } while (0)
; #define PG8_MMA(ai, bj, At, Bt) do { __builtin_amdgcn_s_setprio(1); _Pragma("unroll") for (int m = 0; m < 4; ++m) _Pragma("unroll") for (int n = 0; n < 2; ++n) _Pragma("unroll") for (int k = 0; k < 2; ++k) \
;         acc[ai][bj][m][n] = __builtin_amdgcn_mfma_f32_16x16x32_bf16(Bt[n][k], At[m][k], acc[ai][bj][m][n], 0, 0, 0); __builtin_amdgcn_s_setprio(0); } while (0)
; #define PG8_WAIT_V(n) asm volatile("s_waitcnt vmcnt(" #n ")" ::: "memory")
; #define PG8_WAIT_L(n) asm volatile("s_waitcnt lgkmcnt(" #n ")" ::: "memory")
; #define PG8_BAR __builtin_amdgcn_s_barrier()
; #define PG8_SCHED __builtin_amdgcn_sched_barrier(0)
; template <class Epi, class Sched>
; __device__ __forceinline__ void gemm_phase(LAS unsigned char* lds, const Gemm g, const Sched& S, const Epi& E) {
;     ...
;             PG8_WAIT_V(8); PG8_WAIT_L(0); PG8_BAR; PG8_MMA(1, 0, At, B0); PG8_MMA(1, 1, At, B1); PG8_BAR; PG8_SCHED;
;             PG8_LDB(B0, 1, 0); PG8_LDB(B1, 1, 1); PG8_SCHED; PG8_LDA(At, 1, 0); PG8_STAGE(PG8_SA(0, 1), a2 + hA, voffA);
;             PG8_WAIT_V(8); PG8_WAIT_L(0); PG8_BAR; PG8_MMA(0, 0, At, B0); PG8_MMA(0, 1, At, B1); PG8_BAR; PG8_SCHED;
	s_setprio 0
	s_waitcnt lgkmcnt(0)
	v_mfma_f32_16x16x32_bf16 v[60:63], v[128:131], v[184:187], v[60:63]
	v_mfma_f32_16x16x32_bf16 v[56:59], v[136:139], v[184:187], v[56:59]
	v_mfma_f32_16x16x32_bf16 v[44:47], v[128:131], v[192:195], v[44:47]
	v_mfma_f32_16x16x32_bf16 v[40:43], v[136:139], v[192:195], v[40:43]
	v_mfma_f32_16x16x32_bf16 v[28:31], v[128:131], v[200:203], v[28:31]
	v_mfma_f32_16x16x32_bf16 v[24:27], v[136:139], v[200:203], v[24:27]
	v_mfma_f32_16x16x32_bf16 v[12:15], v[128:131], v[208:211], v[12:15]
	v_mfma_f32_16x16x32_bf16 v[8:11], v[136:139], v[208:211], v[8:11]
	v_mfma_f32_16x16x32_bf16 v[60:63], v[132:135], v[188:191], v[60:63]
	v_mfma_f32_16x16x32_bf16 v[56:59], v[140:143], v[188:191], v[56:59]
	v_mfma_f32_16x16x32_bf16 v[44:47], v[132:135], v[196:199], v[44:47]
	v_mfma_f32_16x16x32_bf16 v[40:43], v[140:143], v[196:199], v[40:43]
	v_mfma_f32_16x16x32_bf16 v[28:31], v[132:135], v[204:207], v[28:31]
	v_mfma_f32_16x16x32_bf16 v[24:27], v[140:143], v[204:207], v[24:27]
	v_mfma_f32_16x16x32_bf16 v[12:15], v[132:135], v[212:215], v[12:15]
	v_mfma_f32_16x16x32_bf16 v[8:11], v[140:143], v[212:215], v[8:11]
	s_setprio 0
	s_setprio 0
	v_mfma_f32_16x16x32_bf16 v[52:55], v[168:171], v[184:187], v[52:55]
	v_mfma_f32_16x16x32_bf16 v[48:51], v[176:179], v[184:187], v[48:51]
	v_mfma_f32_16x16x32_bf16 v[36:39], v[168:171], v[192:195], v[36:39]
	v_mfma_f32_16x16x32_bf16 v[32:35], v[176:179], v[192:195], v[32:35]
	v_mfma_f32_16x16x32_bf16 v[20:23], v[168:171], v[200:203], v[20:23]
	v_mfma_f32_16x16x32_bf16 v[16:19], v[176:179], v[200:203], v[16:19]
	v_mfma_f32_16x16x32_bf16 v[4:7], v[168:171], v[208:211], v[4:7]
	v_mfma_f32_16x16x32_bf16 v[0:3], v[176:179], v[208:211], v[0:3]
	v_mfma_f32_16x16x32_bf16 v[52:55], v[172:175], v[188:191], v[52:55]
	v_mfma_f32_16x16x32_bf16 v[48:51], v[180:183], v[188:191], v[48:51]
	v_mfma_f32_16x16x32_bf16 v[36:39], v[172:175], v[196:199], v[36:39]
	v_mfma_f32_16x16x32_bf16 v[32:35], v[180:183], v[196:199], v[32:35]
	v_mfma_f32_16x16x32_bf16 v[20:23], v[172:175], v[204:207], v[20:23]
	v_mfma_f32_16x16x32_bf16 v[16:19], v[180:183], v[204:207], v[16:19]
	v_mfma_f32_16x16x32_bf16 v[4:7], v[172:175], v[212:215], v[4:7]
	v_mfma_f32_16x16x32_bf16 v[0:3], v[180:183], v[212:215], v[0:3]
	s_setprio 0
	s_barrier
	s_add_i32 s56, 0, 0x18000
	s_add_i32 s57, 0, 0x1c000
	v_add_u32_e32 v140, s56, v163
	v_add_u32_e32 v180, s57, v163
	ds_read_b128 v[128:131], v140
	ds_read_b128 v[132:135], v140 offset:1024
	ds_read_b128 v[136:139], v140 offset:2048
	ds_read_b128 v[140:143], v140 offset:3072
	ds_read_b128 v[168:171], v180
	ds_read_b128 v[172:175], v180 offset:1024
	ds_read_b128 v[176:179], v180 offset:2048
	ds_read_b128 v[180:183], v180 offset:3072
	s_add_u32 s28, s28, 0x160000
	s_addc_u32 s29, s29, 0
	s_mov_b32 m0, s35
	v_lshl_add_u64 v[222:223], s[28:29], 0, v[144:145]
	ds_read_b128 v[184:187], v167 offset:32768
	ds_read_b128 v[188:191], v167 offset:33792
	ds_read_b128 v[192:195], v167 offset:34816
	ds_read_b128 v[196:199], v167 offset:35840
	ds_read_b128 v[200:203], v167 offset:36864
	ds_read_b128 v[204:207], v167 offset:37888
	ds_read_b128 v[208:211], v167 offset:38912
	ds_read_b128 v[212:215], v167 offset:39936
	global_load_lds_dwordx4 v[222:223], off
	v_lshl_add_u64 v[222:223], s[28:29], 0, v[148:149]
	s_mov_b32 m0, s36
	s_nop 0
	global_load_lds_dwordx4 v[222:223], off
	s_waitcnt vmcnt(8)
	s_waitcnt lgkmcnt(0)
	s_barrier
	s_setprio 0
	s_waitcnt lgkmcnt(0)
	v_mfma_f32_16x16x32_bf16 v[124:127], v[128:131], v[184:187], v[124:127]
	v_mfma_f32_16x16x32_bf16 v[120:123], v[136:139], v[184:187], v[120:123]
	v_mfma_f32_16x16x32_bf16 v[108:111], v[128:131], v[192:195], v[108:111]
	v_mfma_f32_16x16x32_bf16 v[104:107], v[136:139], v[192:195], v[104:107]
	v_mfma_f32_16x16x32_bf16 v[92:95], v[128:131], v[200:203], v[92:95]
	v_mfma_f32_16x16x32_bf16 v[88:91], v[136:139], v[200:203], v[88:91]
	v_mfma_f32_16x16x32_bf16 v[76:79], v[128:131], v[208:211], v[76:79]
	v_mfma_f32_16x16x32_bf16 v[72:75], v[136:139], v[208:211], v[72:75]
	v_mfma_f32_16x16x32_bf16 v[124:127], v[132:135], v[188:191], v[124:127]
	v_mfma_f32_16x16x32_bf16 v[120:123], v[140:143], v[188:191], v[120:123]
	v_mfma_f32_16x16x32_bf16 v[108:111], v[132:135], v[196:199], v[108:111]
	v_mfma_f32_16x16x32_bf16 v[104:107], v[140:143], v[196:199], v[104:107]
	v_mfma_f32_16x16x32_bf16 v[92:95], v[132:135], v[204:207], v[92:95]
	v_mfma_f32_16x16x32_bf16 v[88:91], v[140:143], v[204:207], v[88:91]
	v_mfma_f32_16x16x32_bf16 v[76:79], v[132:135], v[212:215], v[76:79]
	v_mfma_f32_16x16x32_bf16 v[72:75], v[140:143], v[212:215], v[72:75]
	s_setprio 0
	s_setprio 0
	v_mfma_f32_16x16x32_bf16 v[116:119], v[168:171], v[184:187], v[116:119]
	v_mfma_f32_16x16x32_bf16 v[112:115], v[176:179], v[184:187], v[112:115]
	v_mfma_f32_16x16x32_bf16 v[100:103], v[168:171], v[192:195], v[100:103]
	v_mfma_f32_16x16x32_bf16 v[96:99], v[176:179], v[192:195], v[96:99]
	v_mfma_f32_16x16x32_bf16 v[84:87], v[168:171], v[200:203], v[84:87]
	v_mfma_f32_16x16x32_bf16 v[80:83], v[176:179], v[200:203], v[80:83]
	v_mfma_f32_16x16x32_bf16 v[68:71], v[168:171], v[208:211], v[68:71]
	v_mfma_f32_16x16x32_bf16 v[64:67], v[176:179], v[208:211], v[64:67]
	v_mfma_f32_16x16x32_bf16 v[116:119], v[172:175], v[188:191], v[116:119]
	v_mfma_f32_16x16x32_bf16 v[112:115], v[180:183], v[188:191], v[112:115]
	v_mfma_f32_16x16x32_bf16 v[100:103], v[172:175], v[196:199], v[100:103]
	v_mfma_f32_16x16x32_bf16 v[96:99], v[180:183], v[196:199], v[96:99]
	v_mfma_f32_16x16x32_bf16 v[84:87], v[172:175], v[204:207], v[84:87]
	v_mfma_f32_16x16x32_bf16 v[80:83], v[180:183], v[204:207], v[80:83]
	v_mfma_f32_16x16x32_bf16 v[68:71], v[172:175], v[212:215], v[68:71]
	v_mfma_f32_16x16x32_bf16 v[64:67], v[180:183], v[212:215], v[64:67]
	s_setprio 0
	s_barrier
; #define PG8_STAGE(bufoff, gbase, voff) do { _Pragma("unroll") for (int _i = 0; _i < 2; ++_i) \
;         __builtin_amdgcn_global_load_lds((const unsigned*)((const char*)(gbase) + (voff)[_i]), (LAS unsigned*)(lds + (bufoff) + ldsw + _i * 8192), 16, 0, 0); } while (0)
; #define PG8_LDA(dst, b, h) do { _Pragma("unroll") for (int m = 0; m < 4; ++m) _Pragma("unroll") for (int k = 0; k < 2; ++k) dst[m][k] = *(const LAS bf16x8*)(lds + PG8_SA(b, h) + aoff + m * 2048 + k * 1024); } while (0)
; #define PG8_MMA(ai, bj, At, Bt) do { __builtin_amdgcn_s_setprio(1); _Pragma("unroll") for (int m = 0; m < 4; ++m) _Pragma("unroll") for (int n = 0; n < 2; ++n) _Pragma("unroll") for (int k = 0; k < 2; ++k) \
;         acc[ai][bj][m][n] = __builtin_amdgcn_mfma_f32_16x16x32_bf16(Bt[n][k], At[m][k], acc[ai][bj][m][n], 0, 0, 0); __builtin_amdgcn_s_setprio(0); } while (0)
; #define PG8_WAIT_V(n) asm volatile("s_waitcnt vmcnt(" #n ")" ::: "memory")
; #define PG8_WAIT_L(n) asm volatile("s_waitcnt lgkmcnt(" #n ")" ::: "memory")
; #define PG8_BAR __builtin_amdgcn_s_barrier()
; #define PG8_SCHED __builtin_amdgcn_sched_barrier(0)
; template <class Epi, class Sched>
; __device__ __forceinline__ void gemm_phase(LAS unsigned char* lds, const Gemm g, const Sched& S, const Epi& E) {
;     ...
;             PG8_LDA(At, 1, 1); PG8_STAGE(PG8_SB(1, 0), b3, voffB); PG8_STAGE(PG8_SB(1, 1), b3 + hB, voffB); PG8_STAGE(PG8_SA(1, 0), a3, voffA);
;             PG8_WAIT_V(8); PG8_WAIT_L(0); PG8_BAR; PG8_MMA(1, 0, At, B0); PG8_MMA(1, 1, At, B1); PG8_BAR; PG8_SCHED;
;         }
;         if (wr == 0) PG8_BAR;
	s_add_i32 s28, s56, s30
	v_lshl_add_u64 v[160:161], v[160:161], 0, s[8:9]
	s_mov_b32 m0, s28
	ds_read_b128 v[184:187], v167 offset:49152
	ds_read_b128 v[188:191], v167 offset:50176
	ds_read_b128 v[192:195], v167 offset:51200
	ds_read_b128 v[196:199], v167 offset:52224
	ds_read_b128 v[200:203], v167 offset:53248
	ds_read_b128 v[204:207], v167 offset:54272
	ds_read_b128 v[208:211], v167 offset:55296
	ds_read_b128 v[212:215], v167 offset:56320
	global_load_lds_dwordx4 v[160:161], off
	s_add_i32 m0, s28, 0x2000
	s_add_u32 s26, s26, 0x160080
	v_lshl_add_u64 v[160:161], v[216:217], 0, s[8:9]
	s_addc_u32 s27, s27, 0
	s_add_i32 s28, s57, s30
	global_load_lds_dwordx4 v[160:161], off
	v_lshl_add_u64 v[160:161], s[26:27], 0, v[146:147]
	s_mov_b32 m0, s28
	s_nop 0
	global_load_lds_dwordx4 v[160:161], off
	v_lshl_add_u64 v[160:161], s[26:27], 0, v[150:151]
	s_add_i32 m0, s28, 0x2000
	s_nop 0
	global_load_lds_dwordx4 v[160:161], off
	v_lshl_add_u64 v[160:161], v[218:219], 0, s[8:9]
	s_mov_b32 m0, s41
	s_nop 0
	global_load_lds_dwordx4 v[160:161], off
	v_lshl_add_u64 v[160:161], v[220:221], 0, s[8:9]
	s_mov_b32 m0, s42
	s_nop 0
	global_load_lds_dwordx4 v[160:161], off
	s_waitcnt vmcnt(8)
	s_waitcnt lgkmcnt(0)
	s_barrier
	s_setprio 0
	s_waitcnt lgkmcnt(0)
	v_mfma_f32_16x16x32_bf16 v[60:63], v[128:131], v[184:187], v[60:63]
	v_mfma_f32_16x16x32_bf16 v[56:59], v[136:139], v[184:187], v[56:59]
	v_mfma_f32_16x16x32_bf16 v[44:47], v[128:131], v[192:195], v[44:47]
	v_mfma_f32_16x16x32_bf16 v[40:43], v[136:139], v[192:195], v[40:43]
	v_mfma_f32_16x16x32_bf16 v[28:31], v[128:131], v[200:203], v[28:31]
	v_mfma_f32_16x16x32_bf16 v[24:27], v[136:139], v[200:203], v[24:27]
	v_mfma_f32_16x16x32_bf16 v[12:15], v[128:131], v[208:211], v[12:15]
	v_mfma_f32_16x16x32_bf16 v[8:11], v[136:139], v[208:211], v[8:11]
	v_mfma_f32_16x16x32_bf16 v[60:63], v[132:135], v[188:191], v[60:63]
	v_mfma_f32_16x16x32_bf16 v[56:59], v[140:143], v[188:191], v[56:59]
	v_mfma_f32_16x16x32_bf16 v[44:47], v[132:135], v[196:199], v[44:47]
	v_mfma_f32_16x16x32_bf16 v[40:43], v[140:143], v[196:199], v[40:43]
	v_mfma_f32_16x16x32_bf16 v[28:31], v[132:135], v[204:207], v[28:31]
	v_mfma_f32_16x16x32_bf16 v[24:27], v[140:143], v[204:207], v[24:27]
	v_mfma_f32_16x16x32_bf16 v[12:15], v[132:135], v[212:215], v[12:15]
	v_mfma_f32_16x16x32_bf16 v[8:11], v[140:143], v[212:215], v[8:11]
	s_setprio 0
	s_setprio 0
	v_mfma_f32_16x16x32_bf16 v[52:55], v[168:171], v[184:187], v[52:55]
	v_mfma_f32_16x16x32_bf16 v[48:51], v[176:179], v[184:187], v[48:51]
	v_mfma_f32_16x16x32_bf16 v[36:39], v[168:171], v[192:195], v[36:39]
	v_mfma_f32_16x16x32_bf16 v[32:35], v[176:179], v[192:195], v[32:35]
	v_mfma_f32_16x16x32_bf16 v[20:23], v[168:171], v[200:203], v[20:23]
	v_mfma_f32_16x16x32_bf16 v[16:19], v[176:179], v[200:203], v[16:19]
	v_mfma_f32_16x16x32_bf16 v[4:7], v[168:171], v[208:211], v[4:7]
	v_mfma_f32_16x16x32_bf16 v[0:3], v[176:179], v[208:211], v[0:3]
	v_mfma_f32_16x16x32_bf16 v[52:55], v[172:175], v[188:191], v[52:55]
	v_mfma_f32_16x16x32_bf16 v[48:51], v[180:183], v[188:191], v[48:51]
	v_mfma_f32_16x16x32_bf16 v[36:39], v[172:175], v[196:199], v[36:39]
	v_mfma_f32_16x16x32_bf16 v[32:35], v[180:183], v[196:199], v[32:35]
	v_mfma_f32_16x16x32_bf16 v[20:23], v[172:175], v[204:207], v[20:23]
	v_mfma_f32_16x16x32_bf16 v[16:19], v[180:183], v[204:207], v[16:19]
	v_mfma_f32_16x16x32_bf16 v[4:7], v[172:175], v[212:215], v[4:7]
	v_mfma_f32_16x16x32_bf16 v[0:3], v[180:183], v[212:215], v[0:3]
	s_setprio 0
	s_barrier
	s_add_i32 s55, s55, 2
	s_add_u32 s24, s24, 0x100
	s_addc_u32 s25, s25, 0
	s_add_u32 s53, s53, 0x100
	s_addc_u32 s54, s54, 0
	s_cmpk_gt_u32 s55, 0x55
	s_cbranch_scc0 .LBB0_1048
	s_and_b64 vcc, exec, s[10:11]
	s_cbranch_vccz .LBB0_1051
	s_barrier
